# v053 idle CUs of the glu and top-k phases convert weight items too (barrier sequence down to 47360 items)
# baseline (speedup 1.0000x reference)
; DEV void phase_prologue_a(const Frame& F0) {
;     ...
;         constexpr int D_ITEMS = (FF / 64) * 32;
;         for (int it = F.gw; it < NE * D_ITEMS; it += F.NGW) { const int e = it / D_ITEMS, r = it % D_ITEMS, kb = r / 32, nb = r % 32;
;             tr_item(GIN(I_WDOWN) + ((size_t)l * NE + e) * FF * 1024, 1024, 32 * nb, 64 * kb, (bf16_t*)(F.ws + WS_WD) + ((size_t)l * NE + e) * 1024 * FF, FF, 32 * nb, scr, F.lane); }
.Lpro_dn_do:
	s_lshl_b64 s[20:21], s[2:3], 4
	s_mov_b32 s2, s31
	v_readlane_b32 s100, v255, 51
	s_cmp_lg_u32 s100, 0x100
	s_cbranch_scc1 .Lpro_dn_all
	s_cmp_lg_u32 s14, 0
	s_cbranch_scc1 .Lpro_dn_all
	s_add_i32 s2, s2, 0x3700

; #define WAIT_VM(n) do {} while (0)
; #define LAUNDER_S(x) do {} while (0)
; #define WAIT_VM(n) asm volatile("s_waitcnt vmcnt(" #n ")" ::: "memory")
; #define LAUNDER_S(x) asm volatile("" : "+s"(x))
; DEV int lane_id() { return (int)__builtin_amdgcn_mbcnt_hi(~0u, __builtin_amdgcn_mbcnt_lo(~0u, 0u)); }
; DEV void xcd_barrier(const XcdBarrier& b) {
;     WAIT_VM(0);
;     __syncthreads();
;     int bw = b.wave; LAUNDER_S(bw);
;     if (bw == 0 && lane_id() == 0) {
; DEV void phase_prologue_a(const Frame& F0) {
;     ...
;         constexpr int GU_NB = 2 * FF / 32, GU_ITEMS = 16 * GU_NB;
;         for (int it = F.gw; it < NE * GU_ITEMS; it += F.NGW) { const int e = it / GU_ITEMS, r = it % GU_ITEMS, kb = r / GU_NB, nb = r % GU_NB; const int d0 = 32 * nb, j = d0 >> 8, w = d0 & 255;
.LBB0_115:
	s_or_b64 exec, exec, s[30:31]
	s_cselect_b32 s38, 1, 0
	v_writelane_b32 v255, s38, 61
	v_readlane_b32 s38, v255, 59
	s_add_i32 s39, s38, 1
	v_writelane_b32 v255, s39, 59
	s_mov_b32 s41, 0
	v_readlane_b32 s39, v251, 29
	s_cmp_eq_u32 s39, 0
	s_cbranch_scc1 .Lbw0_none
	v_readlane_b32 s40, v255, 51
	s_cmp_lg_u32 s40, 0x100
	s_cbranch_scc1 .Lbw0_none
	v_readlane_b32 s40, v255, 48
	s_mul_i32 s40, s40, 7
	s_mul_i32 s38, s38, 0x700
	s_add_i32 s40, s40, s38
	s_add_i32 s40, s40, s39
	s_add_i32 s40, s40, -1
	s_cmp_lt_u32 s40, 0xb900
	s_cbranch_scc0 .Lbw0_none
	s_mov_b32 s41, 0
	s_add_i32 s40, s40, 0x3c00
	s_cmp_lt_u32 s40, 0x7800
	s_cbranch_scc1 .Lbw0_have
	s_mov_b32 s41, 1
	s_sub_i32 s40, s40, 0x7800
	s_cmp_lt_u32 s40, 0x4400
	s_cbranch_scc1 .Lbw0_have
	s_mov_b32 s41, 2
	s_sub_i32 s40, s40, 0x4400
	s_cmp_lt_u32 s40, 0x1b00
	s_cbranch_scc1 .Lbw0_have
	s_mov_b32 s41, 3
	s_sub_i32 s40, s40, 0x1b00

; #define WAIT_VM(n) do {} while (0)
; #define LAUNDER_S(x) do {} while (0)
; #define WAIT_VM(n) asm volatile("s_waitcnt vmcnt(" #n ")" ::: "memory")
; #define LAUNDER_S(x) asm volatile("" : "+s"(x))
; DEV int lane_id() { return (int)__builtin_amdgcn_mbcnt_hi(~0u, __builtin_amdgcn_mbcnt_lo(~0u, 0u)); }
; DEV void xcd_barrier(const XcdBarrier& b) {
;     WAIT_VM(0);
;     __syncthreads();
;     int bw = b.wave; LAUNDER_S(bw);
;     if (bw == 0 && lane_id() == 0) {
; DEV void phase_prologue_a(const Frame& F0) {
;     ...
;         constexpr int GU_NB = 2 * FF / 32, GU_ITEMS = 16 * GU_NB;
;         for (int it = F.gw; it < NE * GU_ITEMS; it += F.NGW) { const int e = it / GU_ITEMS, r = it % GU_ITEMS, kb = r / GU_NB, nb = r % GU_NB; const int d0 = 32 * nb, j = d0 >> 8, w = d0 & 255;
.LBB0_241:
	v_writelane_b32 v253, s58, 51
	s_nop 1
	v_writelane_b32 v253, s59, 52
	v_writelane_b32 v253, s56, 53
	s_nop 1
	v_writelane_b32 v253, s57, 54
	s_or_b64 exec, exec, s[34:35]
	s_cselect_b32 s38, 1, 0
	v_writelane_b32 v255, s38, 61
	v_readlane_b32 s38, v255, 59
	s_add_i32 s39, s38, 1
	v_writelane_b32 v255, s39, 59
	s_mov_b32 s41, 0
	v_readlane_b32 s39, v251, 29
	s_cmp_eq_u32 s39, 0
	s_cbranch_scc1 .Lbw2_none
	v_readlane_b32 s40, v255, 51
	s_cmp_lg_u32 s40, 0x100
	s_cbranch_scc1 .Lbw2_none
	v_readlane_b32 s40, v255, 48
	s_mul_i32 s40, s40, 7
	s_mul_i32 s38, s38, 0x700
	s_add_i32 s40, s40, s38
	s_add_i32 s40, s40, s39
	s_add_i32 s40, s40, -1
	s_cmp_lt_u32 s40, 0xb900
	s_cbranch_scc0 .Lbw2_none
	s_mov_b32 s41, 0
	s_add_i32 s40, s40, 0x3c00
	s_cmp_lt_u32 s40, 0x7800
	s_cbranch_scc1 .Lbw2_have
	s_mov_b32 s41, 1
	s_sub_i32 s40, s40, 0x7800
	s_cmp_lt_u32 s40, 0x4400
	s_cbranch_scc1 .Lbw2_have
	s_mov_b32 s41, 2
	s_sub_i32 s40, s40, 0x4400
	s_cmp_lt_u32 s40, 0x1b00
	s_cbranch_scc1 .Lbw2_have
	s_mov_b32 s41, 3
	s_sub_i32 s40, s40, 0x1b00

; #define WAIT_VM(n) do {} while (0)
; #define LAUNDER_S(x) do {} while (0)
; #define WAIT_VM(n) asm volatile("s_waitcnt vmcnt(" #n ")" ::: "memory")
; #define LAUNDER_S(x) asm volatile("" : "+s"(x))
; DEV int lane_id() { return (int)__builtin_amdgcn_mbcnt_hi(~0u, __builtin_amdgcn_mbcnt_lo(~0u, 0u)); }
; DEV void xcd_barrier(const XcdBarrier& b) {
;     WAIT_VM(0);
;     __syncthreads();
;     int bw = b.wave; LAUNDER_S(bw);
;     if (bw == 0 && lane_id() == 0) {
; DEV void phase_prologue_a(const Frame& F0) {
;     ...
;         constexpr int GU_NB = 2 * FF / 32, GU_ITEMS = 16 * GU_NB;
;         for (int it = F.gw; it < NE * GU_ITEMS; it += F.NGW) { const int e = it / GU_ITEMS, r = it % GU_ITEMS, kb = r / GU_NB, nb = r % GU_NB; const int d0 = 32 * nb, j = d0 >> 8, w = d0 & 255;
.LBB0_422:
	s_or_b64 exec, exec, s[34:35]
	s_cselect_b32 s38, 1, 0
	v_writelane_b32 v255, s38, 61
	v_readlane_b32 s38, v255, 59
	s_add_i32 s39, s38, 1
	v_writelane_b32 v255, s39, 59
	s_mov_b32 s41, 0
	v_readlane_b32 s39, v251, 29
	s_cmp_eq_u32 s39, 0
	s_cbranch_scc1 .Lbw3_none
	v_readlane_b32 s40, v255, 51
	s_cmp_lg_u32 s40, 0x100
	s_cbranch_scc1 .Lbw3_none
	v_readlane_b32 s40, v255, 48
	s_mul_i32 s40, s40, 7
	s_mul_i32 s38, s38, 0x700
	s_add_i32 s40, s40, s38
	s_add_i32 s40, s40, s39
	s_add_i32 s40, s40, -1
	s_cmp_lt_u32 s40, 0xb900
	s_cbranch_scc0 .Lbw3_none
	s_mov_b32 s41, 0
	s_add_i32 s40, s40, 0x3c00
	s_cmp_lt_u32 s40, 0x7800
	s_cbranch_scc1 .Lbw3_have
	s_mov_b32 s41, 1
	s_sub_i32 s40, s40, 0x7800
	s_cmp_lt_u32 s40, 0x4400
	s_cbranch_scc1 .Lbw3_have
	s_mov_b32 s41, 2
	s_sub_i32 s40, s40, 0x4400
	s_cmp_lt_u32 s40, 0x1b00
	s_cbranch_scc1 .Lbw3_have
	s_mov_b32 s41, 3
	s_sub_i32 s40, s40, 0x1b00

; #define WAIT_VM(n) do {} while (0)
; #define LAUNDER_S(x) do {} while (0)
; #define WAIT_VM(n) asm volatile("s_waitcnt vmcnt(" #n ")" ::: "memory")
; #define LAUNDER_S(x) asm volatile("" : "+s"(x))
; DEV int lane_id() { return (int)__builtin_amdgcn_mbcnt_hi(~0u, __builtin_amdgcn_mbcnt_lo(~0u, 0u)); }
; DEV void xcd_barrier(const XcdBarrier& b) {
;     WAIT_VM(0);
;     __syncthreads();
;     int bw = b.wave; LAUNDER_S(bw);
;     if (bw == 0 && lane_id() == 0) {
; DEV void phase_prologue_a(const Frame& F0) {
;     ...
;         constexpr int GU_NB = 2 * FF / 32, GU_ITEMS = 16 * GU_NB;
;         for (int it = F.gw; it < NE * GU_ITEMS; it += F.NGW) { const int e = it / GU_ITEMS, r = it % GU_ITEMS, kb = r / GU_NB, nb = r % GU_NB; const int d0 = 32 * nb, j = d0 >> 8, w = d0 & 255;
.Lxb4_join:
.LBB0_811:
	s_or_b64 exec, exec, s[34:35]
	s_cselect_b32 s38, 1, 0
	v_writelane_b32 v255, s38, 61
	v_readlane_b32 s38, v255, 59
	s_add_i32 s39, s38, 1
	v_writelane_b32 v255, s39, 59
	s_mov_b32 s41, 0
	v_readlane_b32 s39, v251, 29
	s_cmp_eq_u32 s39, 0
	s_cbranch_scc1 .Lbw4_none
	v_readlane_b32 s40, v255, 51
	s_cmp_lg_u32 s40, 0x100
	s_cbranch_scc1 .Lbw4_none
	v_readlane_b32 s40, v255, 48
	s_mul_i32 s40, s40, 7
	s_mul_i32 s38, s38, 0x700
	s_add_i32 s40, s40, s38
	s_add_i32 s40, s40, s39
	s_add_i32 s40, s40, -1
	s_cmp_lt_u32 s40, 0xb900
	s_cbranch_scc0 .Lbw4_none
	s_mov_b32 s41, 0
	s_add_i32 s40, s40, 0x3c00
	s_cmp_lt_u32 s40, 0x7800
	s_cbranch_scc1 .Lbw4_have
	s_mov_b32 s41, 1
	s_sub_i32 s40, s40, 0x7800
	s_cmp_lt_u32 s40, 0x4400
	s_cbranch_scc1 .Lbw4_have
	s_mov_b32 s41, 2
	s_sub_i32 s40, s40, 0x4400
	s_cmp_lt_u32 s40, 0x1b00
	s_cbranch_scc1 .Lbw4_have
	s_mov_b32 s41, 3
	s_sub_i32 s40, s40, 0x1b00

; #define LAS __attribute__((address_space(3)))
; #define NT_LOAD(p) __builtin_nontemporal_load(p)
; DEV void tr_item(const float* W, int ldw, int col0, int k0, bf16_t* WT, int K, int row0, LAS float* scr, int lane) {
; #pragma unroll 8
;     for (int i = 0; i < 32; ++i) { const int kk = 2 * i + (lane >> 5); scr[kk * 33 + (lane & 31)] = NT_LOAD(&W[(size_t)(k0 + kk) * ldw + col0 + (lane & 31)]); }
; DEV void gemm_glu(const Frame& F0, int l, int vcu) {
;     const Frame F = refresh(F0);
;     const int li = l >> 1;
;     pg8::PlainOrder S; S.init((const void*)(F.ws + WS_YS), (const bf16_t*)(F.ws + WS_WGLU) + (size_t)li * 512 * 512, 512, (l == DEPTH - 1) ? LATPAD : MPAD, 512, F.G, vcu);
;     EpiGlu E; E.MG = (bf16_t*)(F.ws + WS_MERGED); E.YS = (const bf16_t*)(F.ws + WS_YS); E.bias = GIN(I_ODBGLU) + li * 512;
;     pg8::gemm_phase(F.lds, 512, S, E, F.wave, F.lane);
; }
.Lbw6_skip:
	s_waitcnt lgkmcnt(0)
	v_readlane_b32 s38, v255, 61
	s_cmp_lg_u32 s38, 0
	s_mov_b64 s[2:3], -1
	s_and_b64 vcc, exec, s[56:57]
	s_waitcnt lgkmcnt(0)
	s_barrier
	s_cbranch_vccz .LBB0_1315
	v_readlane_b32 s4, v251, 0
	v_readlane_b32 s5, v251, 1
	v_readlane_b32 s4, v253, 51
	v_readlane_b32 s5, v253, 52
	s_and_b64 s[4:5], s[4:5], exec
	s_cselect_b32 s33, 64, 0x44
	v_readlane_b32 s6, v251, 2
	v_readlane_b32 s7, v251, 3
	s_lshl_b32 s0, s33, 1
	v_readlane_b32 s12, v251, 29
	v_mov_b32_e32 v16, v200
	s_mov_b64 s[2:3], s[6:7]
	s_cmp_ge_i32 s95, s0
	s_cbranch_scc0 .Lglu_gemm
	v_readlane_b32 s2, v255, 51
	s_cmp_lg_u32 s2, 0x100
	s_cbranch_scc1 .LBB0_1270
	v_readlane_b32 s2, v255, 48
	s_cmp_lt_u32 s2, 0x88
	s_cbranch_scc1 .LBB0_1270
	v_readlane_b32 s36, v253, 62
	v_readlane_b32 s3, v251, 29
	s_sub_i32 s2, s2, 0x88
	s_lshl_b32 s2, s2, 3
	s_add_i32 s2, s2, s3
	v_readlane_b32 s6, v255, 53
	v_readlane_b32 s7, v255, 54
	v_readlane_b32 s4, v255, 55
	v_readlane_b32 s5, v255, 56
	v_readlane_b32 s34, v255, 57
	v_readlane_b32 s35, v255, 58
	s_add_u32 s6, s6, 0x2bc8000
	s_addc_u32 s7, s7, 0
	s_mov_b32 s8, 0x10000000
	s_mov_b32 s37, 0x2b00
	s_cmp_eq_u32 s36, 1
	s_cbranch_scc1 .Lsl_go
	s_mov_b32 s8, 0x18000000
	s_mov_b32 s37, 0x3e00
.Lsl_go:
	s_add_u32 s4, s4, s8
	s_addc_u32 s5, s5, 0
	s_add_u32 s34, s34, s8
	s_addc_u32 s35, s35, 0
	s_add_u32 s6, s6, s8
	s_addc_u32 s7, s7, 0
	s_add_i32 s2, s2, s37
	s_add_i32 s101, s37, 0xf00
	s_lshl_b32 s30, s3, 14
	v_and_b32_e32 v120, 31, v200
	v_lshlrev_b32_e32 v2, 2, v120
	v_lshrrev_b32_e32 v3, 5, v200
	v_and_b32_e32 v4, 7, v200
	v_lshrrev_b32_e32 v6, 3, v200
	v_mul_u32_u24_e32 v7, 33, v3
	v_add_u32_e32 v7, v7, v120
	v_lshl_add_u32 v7, v7, 2, s30
	v_add_u32_e32 v8, 0x400, v7
	v_add_u32_e32 v9, 0x840, v7
	v_add_u32_e32 v10, 0xc40, v7
	v_add_u32_e32 v11, 0x1080, v7
	v_add_u32_e32 v12, 0x1480, v7
	v_add_u32_e32 v13, 0x18c0, v7
	v_add_u32_e32 v14, 0x1cc0, v7
	v_mul_u32_u24_e32 v120, 0x108, v4
	v_add_u32_e32 v120, v120, v6
	v_lshl_add_u32 v15, v120, 2, s30
	v_lshl_add_u32 v122, v3, 13, v2
	v_mov_b32_e32 v123, 0
	v_lshlrev_b32_e32 v124, 4, v4
	v_lshl_add_u32 v124, v6, 11, v124
	v_mov_b32_e32 v125, 0
	s_mov_b64 s[40:41], 0x20000
	s_mov_b64 s[42:43], 0x4000
	s_mov_b64 s[44:45], 0x4000
.Lsl_loop:
	s_lshr_b32 s8, s2, 11
	s_and_b32 s9, s2, 0x7ff
	s_lshr_b32 s10, s9, 7
	s_and_b32 s9, s9, 0x7f
	s_lshl_b32 s24, s10, 19
	s_lshr_b32 s25, s9, 3
	s_lshl_b32 s25, s25, 9
	s_add_i32 s24, s24, s25
	s_and_b32 s25, s9, 3
	s_lshl_b32 s25, s25, 7
	s_add_i32 s24, s24, s25
	s_lshr_b32 s29, s8, 9
	s_lshl_b32 s28, s8, 23
	s_add_u32 s28, s28, s24
	s_addc_u32 s29, s29, 0
	s_bitcmp0_b32 s9, 2
	s_cselect_b32 s24, s4, s34
	s_cselect_b32 s25, s5, s35
	s_add_u32 s28, s28, s24
	s_addc_u32 s29, s29, s25
	s_lshl_b32 s24, s9, 16
	s_lshl_b32 s25, s10, 7
	s_add_i32 s24, s24, s25
	s_lshr_b32 s11, s8, 9
	s_lshl_b32 s10, s8, 23
	s_add_u32 s10, s10, s24
	s_addc_u32 s11, s11, 0
	s_add_u32 s10, s10, s6
	s_addc_u32 s11, s11, s7
	v_lshl_add_u64 v[16:17], s[28:29], 0, v[122:123]
	v_lshl_add_u64 v[18:19], v[16:17], 0, s[44:45]
	v_lshl_add_u64 v[20:21], v[18:19], 0, s[44:45]
	v_lshl_add_u64 v[22:23], v[20:21], 0, s[44:45]
	v_lshl_add_u64 v[24:25], v[22:23], 0, s[44:45]
	v_lshl_add_u64 v[26:27], v[24:25], 0, s[44:45]
	v_lshl_add_u64 v[28:29], v[26:27], 0, s[44:45]
	v_lshl_add_u64 v[30:31], v[28:29], 0, s[44:45]
	global_load_dword v32, v[16:17], off nt
	global_load_dword v33, v[18:19], off nt
	global_load_dword v34, v[20:21], off nt
	global_load_dword v35, v[22:23], off nt
	global_load_dword v36, v[24:25], off nt
	global_load_dword v37, v[26:27], off nt
	global_load_dword v38, v[28:29], off nt
	global_load_dword v39, v[30:31], off nt
	v_lshl_add_u64 v[16:17], v[16:17], 0, s[40:41]
	v_lshl_add_u64 v[18:19], v[18:19], 0, s[40:41]
	v_lshl_add_u64 v[20:21], v[20:21], 0, s[40:41]
	v_lshl_add_u64 v[22:23], v[22:23], 0, s[40:41]
	v_lshl_add_u64 v[24:25], v[24:25], 0, s[40:41]
	v_lshl_add_u64 v[26:27], v[26:27], 0, s[40:41]
	v_lshl_add_u64 v[28:29], v[28:29], 0, s[40:41]
	v_lshl_add_u64 v[30:31], v[30:31], 0, s[40:41]
	global_load_dword v40, v[16:17], off nt
	global_load_dword v41, v[18:19], off nt
	global_load_dword v42, v[20:21], off nt
	global_load_dword v43, v[22:23], off nt
	global_load_dword v44, v[24:25], off nt
	global_load_dword v45, v[26:27], off nt
	global_load_dword v46, v[28:29], off nt
	global_load_dword v47, v[30:31], off nt
	v_lshl_add_u64 v[16:17], v[16:17], 0, s[40:41]
	v_lshl_add_u64 v[18:19], v[18:19], 0, s[40:41]
	v_lshl_add_u64 v[20:21], v[20:21], 0, s[40:41]
	v_lshl_add_u64 v[22:23], v[22:23], 0, s[40:41]
	v_lshl_add_u64 v[24:25], v[24:25], 0, s[40:41]
	v_lshl_add_u64 v[26:27], v[26:27], 0, s[40:41]
	v_lshl_add_u64 v[28:29], v[28:29], 0, s[40:41]
	v_lshl_add_u64 v[30:31], v[30:31], 0, s[40:41]
	global_load_dword v48, v[16:17], off nt
	global_load_dword v49, v[18:19], off nt
	global_load_dword v50, v[20:21], off nt
	global_load_dword v51, v[22:23], off nt
	global_load_dword v52, v[24:25], off nt
	global_load_dword v53, v[26:27], off nt
	global_load_dword v54, v[28:29], off nt
	global_load_dword v55, v[30:31], off nt
	v_lshl_add_u64 v[16:17], v[16:17], 0, s[40:41]
	v_lshl_add_u64 v[18:19], v[18:19], 0, s[40:41]
	v_lshl_add_u64 v[20:21], v[20:21], 0, s[40:41]
	v_lshl_add_u64 v[22:23], v[22:23], 0, s[40:41]
	v_lshl_add_u64 v[24:25], v[24:25], 0, s[40:41]
	v_lshl_add_u64 v[26:27], v[26:27], 0, s[40:41]
	v_lshl_add_u64 v[28:29], v[28:29], 0, s[40:41]
	v_lshl_add_u64 v[30:31], v[30:31], 0, s[40:41]
	global_load_dword v56, v[16:17], off nt
	global_load_dword v57, v[18:19], off nt
	global_load_dword v58, v[20:21], off nt
	global_load_dword v59, v[22:23], off nt
; #define WAVE_LDS_SYNC() do { int _z = 0; (void)emu::wave_xchg(&_z, 4); } while (0)
; #define LAS __attribute__((address_space(3)))
; #define WAVE_LDS_SYNC() asm volatile("s_waitcnt lgkmcnt(0)" ::: "memory")
; #define NT_LOAD(p) __builtin_nontemporal_load(p)
; DEV void tr_item(const float* W, int ldw, int col0, int k0, bf16_t* WT, int K, int row0, LAS float* scr, int lane) {
; #pragma unroll 8
;     for (int i = 0; i < 32; ++i) { const int kk = 2 * i + (lane >> 5); scr[kk * 33 + (lane & 31)] = NT_LOAD(&W[(size_t)(k0 + kk) * ldw + col0 + (lane & 31)]); }
;     WAVE_LDS_SYNC();
;     const int c = lane & 7;
; #pragma unroll
;     for (int j = 0; j < 4; ++j) { const int n = (lane >> 3) + 8 * j; const LAS float* s = scr + (8 * c) * 33 + n;
	global_load_dword v60, v[24:25], off nt
	global_load_dword v61, v[26:27], off nt
	global_load_dword v62, v[28:29], off nt
	global_load_dword v63, v[30:31], off nt
	v_lshl_add_u64 v[64:65], s[10:11], 0, v[124:125]
	v_lshl_add_u64 v[66:67], v[64:65], 0, s[42:43]
	v_lshl_add_u64 v[68:69], v[66:67], 0, s[42:43]
	v_lshl_add_u64 v[70:71], v[68:69], 0, s[42:43]
	s_add_i32 s31, s2, 0x3c0
	s_lshr_b32 s8, s31, 11
	s_and_b32 s9, s31, 0x7ff
	s_lshr_b32 s10, s9, 7
	s_and_b32 s9, s9, 0x7f
	s_lshl_b32 s24, s10, 19
	s_lshr_b32 s25, s9, 3
	s_lshl_b32 s25, s25, 9
	s_add_i32 s24, s24, s25
	s_and_b32 s25, s9, 3
	s_lshl_b32 s25, s25, 7
	s_add_i32 s24, s24, s25
	s_lshr_b32 s29, s8, 9
	s_lshl_b32 s28, s8, 23
	s_add_u32 s28, s28, s24
	s_addc_u32 s29, s29, 0
	s_bitcmp0_b32 s9, 2
	s_cselect_b32 s24, s4, s34
	s_cselect_b32 s25, s5, s35
	s_add_u32 s28, s28, s24
	s_addc_u32 s29, s29, s25
	s_lshl_b32 s24, s9, 16
	s_lshl_b32 s25, s10, 7
	s_add_i32 s24, s24, s25
	s_lshr_b32 s11, s8, 9
	s_lshl_b32 s10, s8, 23
	s_add_u32 s10, s10, s24
	s_addc_u32 s11, s11, 0
	s_add_u32 s10, s10, s6
	s_addc_u32 s11, s11, s7
	v_lshl_add_u64 v[16:17], s[28:29], 0, v[122:123]
	v_lshl_add_u64 v[18:19], v[16:17], 0, s[44:45]
	v_lshl_add_u64 v[20:21], v[18:19], 0, s[44:45]
	v_lshl_add_u64 v[22:23], v[20:21], 0, s[44:45]
	v_lshl_add_u64 v[24:25], v[22:23], 0, s[44:45]
	v_lshl_add_u64 v[26:27], v[24:25], 0, s[44:45]
	v_lshl_add_u64 v[28:29], v[26:27], 0, s[44:45]
	v_lshl_add_u64 v[30:31], v[28:29], 0, s[44:45]
	global_load_dword v162, v[16:17], off nt
	global_load_dword v163, v[18:19], off nt
	global_load_dword v164, v[20:21], off nt
	global_load_dword v165, v[22:23], off nt
	global_load_dword v166, v[24:25], off nt
	global_load_dword v167, v[26:27], off nt
	global_load_dword v168, v[28:29], off nt
	global_load_dword v169, v[30:31], off nt
	v_lshl_add_u64 v[16:17], v[16:17], 0, s[40:41]
	v_lshl_add_u64 v[18:19], v[18:19], 0, s[40:41]
	v_lshl_add_u64 v[20:21], v[20:21], 0, s[40:41]
	v_lshl_add_u64 v[22:23], v[22:23], 0, s[40:41]
	v_lshl_add_u64 v[24:25], v[24:25], 0, s[40:41]
	v_lshl_add_u64 v[26:27], v[26:27], 0, s[40:41]
	v_lshl_add_u64 v[28:29], v[28:29], 0, s[40:41]
	v_lshl_add_u64 v[30:31], v[30:31], 0, s[40:41]
	global_load_dword v170, v[16:17], off nt
	global_load_dword v171, v[18:19], off nt
	global_load_dword v172, v[20:21], off nt
	global_load_dword v173, v[22:23], off nt
	global_load_dword v174, v[24:25], off nt
	global_load_dword v175, v[26:27], off nt
	global_load_dword v176, v[28:29], off nt
	global_load_dword v177, v[30:31], off nt
	v_lshl_add_u64 v[16:17], v[16:17], 0, s[40:41]
	v_lshl_add_u64 v[18:19], v[18:19], 0, s[40:41]
	v_lshl_add_u64 v[20:21], v[20:21], 0, s[40:41]
	v_lshl_add_u64 v[22:23], v[22:23], 0, s[40:41]
	v_lshl_add_u64 v[24:25], v[24:25], 0, s[40:41]
	v_lshl_add_u64 v[26:27], v[26:27], 0, s[40:41]
	v_lshl_add_u64 v[28:29], v[28:29], 0, s[40:41]
	v_lshl_add_u64 v[30:31], v[30:31], 0, s[40:41]
	global_load_dword v178, v[16:17], off nt
	global_load_dword v179, v[18:19], off nt
	global_load_dword v180, v[20:21], off nt
	global_load_dword v181, v[22:23], off nt
	global_load_dword v182, v[24:25], off nt
	global_load_dword v183, v[26:27], off nt
	global_load_dword v184, v[28:29], off nt
	global_load_dword v185, v[30:31], off nt
	v_lshl_add_u64 v[16:17], v[16:17], 0, s[40:41]
	v_lshl_add_u64 v[18:19], v[18:19], 0, s[40:41]
	v_lshl_add_u64 v[20:21], v[20:21], 0, s[40:41]
	v_lshl_add_u64 v[22:23], v[22:23], 0, s[40:41]
	v_lshl_add_u64 v[24:25], v[24:25], 0, s[40:41]
	v_lshl_add_u64 v[26:27], v[26:27], 0, s[40:41]
	v_lshl_add_u64 v[28:29], v[28:29], 0, s[40:41]
	v_lshl_add_u64 v[30:31], v[30:31], 0, s[40:41]
	global_load_dword v186, v[16:17], off nt
	global_load_dword v187, v[18:19], off nt
	global_load_dword v188, v[20:21], off nt
	global_load_dword v189, v[22:23], off nt
	global_load_dword v190, v[24:25], off nt
	global_load_dword v191, v[26:27], off nt
	global_load_dword v192, v[28:29], off nt
	global_load_dword v193, v[30:31], off nt
	v_lshl_add_u64 v[126:127], s[10:11], 0, v[124:125]
	v_lshl_add_u64 v[128:129], v[126:127], 0, s[42:43]
	v_lshl_add_u64 v[130:131], v[128:129], 0, s[42:43]
	v_lshl_add_u64 v[132:133], v[130:131], 0, s[42:43]
	s_waitcnt vmcnt(62)
	ds_write2_b32 v7, v32, v33 offset1:66
	s_waitcnt vmcnt(60)
	ds_write2_b32 v7, v34, v35 offset0:132 offset1:198
	s_waitcnt vmcnt(58)
	ds_write2_b32 v8, v36, v37 offset0:8 offset1:74
	s_waitcnt vmcnt(56)
	ds_write2_b32 v8, v38, v39 offset0:140 offset1:206
	s_waitcnt vmcnt(54)
	ds_write2_b32 v9, v40, v41 offset1:66
	s_waitcnt vmcnt(52)
	ds_write2_b32 v9, v42, v43 offset0:132 offset1:198
	s_waitcnt vmcnt(50)
	ds_write2_b32 v10, v44, v45 offset0:8 offset1:74
	s_waitcnt vmcnt(48)
	ds_write2_b32 v10, v46, v47 offset0:140 offset1:206
	s_waitcnt vmcnt(46)
	ds_write2_b32 v11, v48, v49 offset1:66
	s_waitcnt vmcnt(44)
	ds_write2_b32 v11, v50, v51 offset0:132 offset1:198
	s_waitcnt vmcnt(42)
	ds_write2_b32 v12, v52, v53 offset0:8 offset1:74
	s_waitcnt vmcnt(40)
	ds_write2_b32 v12, v54, v55 offset0:140 offset1:206
	s_waitcnt vmcnt(38)
	ds_write2_b32 v13, v56, v57 offset1:66
	s_waitcnt vmcnt(36)
	ds_write2_b32 v13, v58, v59 offset0:132 offset1:198
	s_waitcnt vmcnt(34)
	ds_write2_b32 v14, v60, v61 offset0:8 offset1:74
	s_waitcnt vmcnt(32)
	ds_write2_b32 v14, v62, v63 offset0:140 offset1:206
	ds_read2_b32 v[72:73], v15 offset1:8
	ds_read2_b32 v[74:75], v15 offset0:33 offset1:41
	ds_read2_b32 v[76:77], v15 offset0:66 offset1:74
	ds_read2_b32 v[78:79], v15 offset0:99 offset1:107
	ds_read2_b32 v[80:81], v15 offset0:132 offset1:140
	ds_read2_b32 v[82:83], v15 offset0:165 offset1:173
	ds_read2_b32 v[84:85], v15 offset0:198 offset1:206
	ds_read2_b32 v[86:87], v15 offset0:231 offset1:239
	ds_read2_b32 v[88:89], v15 offset0:16 offset1:24
	ds_read2_b32 v[90:91], v15 offset0:49 offset1:57
	ds_read2_b32 v[92:93], v15 offset0:82 offset1:90
	ds_read2_b32 v[94:95], v15 offset0:115 offset1:123
	s_waitcnt lgkmcnt(4)
; #define LAS __attribute__((address_space(3)))
; #define NT_STORE(v, p) __builtin_nontemporal_store((v), (p))
; DEV unsigned pk2(float lo, float hi) { return f2bf(lo) | (f2bf(hi) << 16); }
; DEV unsigned pk2(float lo, float hi) { const f32x2n_t v = {lo, hi}; return __builtin_bit_cast(unsigned, __builtin_convertvector(v, bf16x2n_t)); }
; DEV void tr_item(const float* W, int ldw, int col0, int k0, bf16_t* WT, int K, int row0, LAS float* scr, int lane) {
;     ...
; #pragma unroll
;     for (int j = 0; j < 4; ++j) { const int n = (lane >> 3) + 8 * j; const LAS float* s = scr + (8 * c) * 33 + n;
;         u32x4 o; o.x = pk2(s[0 * 33], s[1 * 33]); o.y = pk2(s[2 * 33], s[3 * 33]); o.z = pk2(s[4 * 33], s[5 * 33]); o.w = pk2(s[6 * 33], s[7 * 33]);
;         NT_STORE(o, (u32x4*)(WT + (size_t)(row0 + n) * K + k0 + 8 * c)); }
	v_cvt_pk_bf16_f32 v104, v72, v74
	v_cvt_pk_bf16_f32 v105, v76, v78
	v_cvt_pk_bf16_f32 v106, v80, v82
	v_cvt_pk_bf16_f32 v107, v84, v86
	v_cvt_pk_bf16_f32 v108, v73, v75
	v_cvt_pk_bf16_f32 v109, v77, v79
	v_cvt_pk_bf16_f32 v110, v81, v83
	v_cvt_pk_bf16_f32 v111, v85, v87
	ds_read2_b32 v[96:97], v15 offset0:148 offset1:156
	ds_read2_b32 v[98:99], v15 offset0:181 offset1:189
	ds_read2_b32 v[100:101], v15 offset0:214 offset1:222
	ds_read2_b32 v[102:103], v15 offset0:247 offset1:255
	global_store_dwordx4 v[64:65], v[104:107], off nt
	global_store_dwordx4 v[66:67], v[108:111], off nt
	s_waitcnt lgkmcnt(0)
	v_cvt_pk_bf16_f32 v112, v88, v90
	v_cvt_pk_bf16_f32 v113, v92, v94
	v_cvt_pk_bf16_f32 v114, v96, v98
	v_cvt_pk_bf16_f32 v115, v100, v102
	v_cvt_pk_bf16_f32 v116, v89, v91
	v_cvt_pk_bf16_f32 v117, v93, v95
	v_cvt_pk_bf16_f32 v118, v97, v99
	v_cvt_pk_bf16_f32 v119, v101, v103
	global_store_dwordx4 v[68:69], v[112:115], off nt
	global_store_dwordx4 v[70:71], v[116:119], off nt
	s_waitcnt vmcnt(34)
	ds_write2_b32 v7, v162, v163 offset1:66
	s_waitcnt vmcnt(32)
	ds_write2_b32 v7, v164, v165 offset0:132 offset1:198
	s_waitcnt vmcnt(30)
	ds_write2_b32 v8, v166, v167 offset0:8 offset1:74
	s_waitcnt vmcnt(28)
	ds_write2_b32 v8, v168, v169 offset0:140 offset1:206
	s_waitcnt vmcnt(26)
	ds_write2_b32 v9, v170, v171 offset1:66
	s_waitcnt vmcnt(24)
	ds_write2_b32 v9, v172, v173 offset0:132 offset1:198
	s_waitcnt vmcnt(22)
	ds_write2_b32 v10, v174, v175 offset0:8 offset1:74
	s_waitcnt vmcnt(20)
	ds_write2_b32 v10, v176, v177 offset0:140 offset1:206
	s_waitcnt vmcnt(18)
	ds_write2_b32 v11, v178, v179 offset1:66
	s_waitcnt vmcnt(16)
	ds_write2_b32 v11, v180, v181 offset0:132 offset1:198
	s_waitcnt vmcnt(14)
	ds_write2_b32 v12, v182, v183 offset0:8 offset1:74
	s_waitcnt vmcnt(12)
	ds_write2_b32 v12, v184, v185 offset0:140 offset1:206
	s_waitcnt vmcnt(10)
	ds_write2_b32 v13, v186, v187 offset1:66
	s_waitcnt vmcnt(8)
	ds_write2_b32 v13, v188, v189 offset0:132 offset1:198
	s_waitcnt vmcnt(6)
	ds_write2_b32 v14, v190, v191 offset0:8 offset1:74
	s_waitcnt vmcnt(4)
	ds_write2_b32 v14, v192, v193 offset0:140 offset1:206
	ds_read2_b32 v[72:73], v15 offset1:8
	ds_read2_b32 v[74:75], v15 offset0:33 offset1:41
	ds_read2_b32 v[76:77], v15 offset0:66 offset1:74
	ds_read2_b32 v[78:79], v15 offset0:99 offset1:107
	ds_read2_b32 v[80:81], v15 offset0:132 offset1:140
	ds_read2_b32 v[82:83], v15 offset0:165 offset1:173
	ds_read2_b32 v[84:85], v15 offset0:198 offset1:206
	ds_read2_b32 v[86:87], v15 offset0:231 offset1:239
	ds_read2_b32 v[88:89], v15 offset0:16 offset1:24
	ds_read2_b32 v[90:91], v15 offset0:49 offset1:57
	ds_read2_b32 v[92:93], v15 offset0:82 offset1:90
	ds_read2_b32 v[94:95], v15 offset0:115 offset1:123
	s_waitcnt lgkmcnt(4)
	v_cvt_pk_bf16_f32 v104, v72, v74
	v_cvt_pk_bf16_f32 v105, v76, v78
	v_cvt_pk_bf16_f32 v106, v80, v82
	v_cvt_pk_bf16_f32 v107, v84, v86
	v_cvt_pk_bf16_f32 v108, v73, v75
	v_cvt_pk_bf16_f32 v109, v77, v79
	v_cvt_pk_bf16_f32 v110, v81, v83
	v_cvt_pk_bf16_f32 v111, v85, v87
	ds_read2_b32 v[96:97], v15 offset0:148 offset1:156
	ds_read2_b32 v[98:99], v15 offset0:181 offset1:189
	ds_read2_b32 v[100:101], v15 offset0:214 offset1:222
	ds_read2_b32 v[102:103], v15 offset0:247 offset1:255
	global_store_dwordx4 v[126:127], v[104:107], off nt
	global_store_dwordx4 v[128:129], v[108:111], off nt
	s_waitcnt lgkmcnt(0)
	v_cvt_pk_bf16_f32 v112, v88, v90
	v_cvt_pk_bf16_f32 v113, v92, v94
	v_cvt_pk_bf16_f32 v114, v96, v98
	v_cvt_pk_bf16_f32 v115, v100, v102
	v_cvt_pk_bf16_f32 v116, v89, v91
	v_cvt_pk_bf16_f32 v117, v93, v95
	v_cvt_pk_bf16_f32 v118, v97, v99
	v_cvt_pk_bf16_f32 v119, v101, v103
	global_store_dwordx4 v[130:131], v[112:115], off nt
	global_store_dwordx4 v[132:133], v[116:119], off nt
	s_add_i32 s2, s2, 0x780
	s_cmp_lt_u32 s2, s101
	s_cbranch_scc1 .Lsl_loop
	s_branch .LBB0_1270
; template <class Epi, class Sched>
; DEV void gemm_phase(LAS unsigned char* lds, const int K, const Sched& S, const Epi& E, const int wid, const int lane) {
;     ...
; #pragma unroll
;     for (int i = 0; i < 2; ++i) { int R, C; stage_rc(tid * 16 + i * 8192, R, C); const int Rb = Epi::PERM ? ((R & ~31) + perm32(R & 31)) : R; Ri[i] = R; Ci[i] = C;
;         voffA[i] = (unsigned)(R * K + C) * 2u; voffB[i] = (unsigned)(Rb * K + C) * 2u; }
;     unsigned goffC[2][2] = {{0u, 0u}, {0u, 0u}}, goffN[2][2] = {{0u, 0u}, {0u, 0u}};
;     constexpr int GIDX_OFF = STAGE_BYTES;
;     const size_t kstep = (size_t)(BK * 2);
;     const size_t hstep = (size_t)HALF * K * 2;
;     const unsigned ldsw = (unsigned)wid * 1024u;
;     const int aoff = lds_byte(wr * 64 + fr, fq * 8), boff = lds_byte(wc * 32 + fr, fq * 8);
;     ...
;     Unit cur, nxt; int ui = 0;
;     if (!S.next(0, cur)) return;
;     f32x4 acc[2][2][4][2];
; #pragma unroll
;     for (int a = 0; a < 2; ++a)
; #pragma unroll
;         for (int b = 0; b < 2; ++b)
; #pragma unroll
;             for (int m = 0; m < 4; ++m)
; #pragma unroll
;                 for (int n = 0; n < 2; ++n) acc[a][b][m][n] = (f32x4){0.f, 0.f, 0.f, 0.f};
;     bf16x8 At[4][2], B0[2][2], B1[2][2];
;     const char* cA = cur.A; const char* cB = cur.B;
;     if constexpr (Sched::GATHER_A) {
; #pragma unroll
;         for (int hh = 0; hh < 2; ++hh)
; #pragma unroll
;             for (int i = 0; i < 2; ++i) { goffC[hh][i] = (unsigned)S.gidx[S.idx_base(cur) + hh * HALF + Ri[i]] * (unsigned)(K * 2) + (unsigned)(Ci[i] * 2); goffN[hh][i] = goffC[hh][i]; }
;     }
;     PG8_STAGE(PG8_SB(0, 0), cB, voffB); PG8_STAGE(PG8_SB(0, 1), cB + hstep, voffB); PG8_STAGEA(PG8_SA(0, 0), cA, 0, false); PG8_STAGEA(PG8_SA(0, 1), cA, 1, false);
;     DEV bool next(int i, Unit& u) const {
;         const long L = (long)i * G + c; if (L >= nwg) return false;
;         int wgid = (int)L; { const int q = nwg / 8, r = nwg % 8, xcd = wgid % 8, off = wgid / 8; wgid = (xcd < r ? xcd * (q + 1) : r * (q + 1) + (xcd - r) * q) + off; }
;         const int nig = 8 * nN, gid = wgid / nig, fm = gid * 8, gsz = (nM - fm) < 8 ? (nM - fm) : 8;
;         u.pm = fm + ((wgid % nig) % gsz); u.pn = (wgid % nig) / gsz; u.e = 0;
;         u.A = A + (size_t)u.pm * BM * K * 2; u.B = Bt + (size_t)u.pn * BM * K * 2; return true;
.Lglu_gemm:
	v_readlane_b32 s4, v253, 62
	s_lshr_b32 s10, s4, 1
	v_readlane_b32 s5, v253, 63
	s_add_u32 s4, s2, 0x3b5a8800
	s_addc_u32 s5, s3, 0
	s_lshl_b32 s6, s10, 19
	s_add_u32 s6, s2, s6
	s_addc_u32 s7, s3, 0
	s_add_u32 s30, s6, 0x2ac8000
	s_addc_u32 s31, s7, 0
	s_lshl_b32 s34, s12, 10
	v_lshl_add_u32 v0, v16, 4, s34
	v_add_u32_e32 v2, 0x2000, v0
	v_ashrrev_i32_e32 v3, 31, v2
	v_lshrrev_b32_e32 v3, 22, v3
	v_add_u32_e32 v3, v2, v3
	v_ashrrev_i32_e32 v10, 10, v3
	v_mul_i32_i24_e32 v3, 0x400, v10
	v_sub_u32_e32 v2, v2, v3
	v_lshrrev_b32_e32 v3, 4, v2
	v_bitop3_b32 v2, v3, v2, 32 bitop3:0x6c
	v_ashrrev_i32_e32 v3, 31, v2
	v_lshrrev_b32_e32 v3, 26, v3
	v_add_u32_e32 v3, v2, v3
	v_ashrrev_i32_e32 v11, 6, v3
	v_lshlrev_b32_e32 v4, 3, v10
	v_and_b32_e32 v3, 0xffc0, v3
	v_and_b32_e32 v4, -16, v4
	v_sub_u32_e32 v2, v2, v3
	v_add_u32_e32 v4, v11, v4
	v_lshrrev_b16_e32 v3, 7, v2
	v_and_b32_e32 v5, 3, v11
	s_mov_b32 s6, 0x3fffe0
	v_lshrrev_b32_e32 v6, 2, v4
	v_lshlrev_b32_e32 v7, 1, v4
	v_and_b32_e32 v3, 1, v3
	v_and_or_b32 v5, v4, s6, v5
	v_and_b32_e32 v6, 4, v6
	v_and_b32_e32 v7, 24, v7
	v_add_u16_e32 v2, v2, v3
	v_or3_b32 v5, v5, v6, v7
	v_lshlrev_b32_e32 v6, 5, v10
	v_ashrrev_i16_sdwa v2, v202, sext(v2) dst_sel:DWORD dst_unused:UNUSED_PAD src0_sel:DWORD src1_sel:BYTE_0
	v_and_b32_e32 v6, 32, v6
	v_bfe_i32 v13, v2, 0, 16
	v_add_lshl_u32 v2, v6, v13, 1
	v_lshl_add_u32 v130, v5, 10, v2
	v_lshl_add_u32 v132, v4, 10, v2
	v_ashrrev_i32_e32 v2, 31, v0
	v_lshrrev_b32_e32 v2, 22, v2
	v_add_u32_e32 v2, v0, v2
	v_ashrrev_i32_e32 v12, 10, v2
	v_mul_i32_i24_e32 v2, 0x400, v12
	v_sub_u32_e32 v0, v0, v2
	v_lshrrev_b32_e32 v2, 4, v0
	v_bitop3_b32 v0, v2, v0, 32 bitop3:0x6c
	v_ashrrev_i32_e32 v2, 31, v0
	v_lshrrev_b32_e32 v2, 26, v2
	v_add_u32_e32 v2, v0, v2
	v_lshlrev_b32_e32 v3, 3, v12
	v_ashrrev_i32_e32 v14, 6, v2
	v_and_b32_e32 v3, -16, v3
	v_add_u32_e32 v3, v14, v3
	v_and_b32_e32 v4, 3, v14
	v_and_or_b32 v4, v3, s6, v4
	s_lshr_b32 s35, s33, 2
	v_readlane_b32 s6, v252, 24
	s_ashr_i32 s13, s12, 2
	s_add_i32 s36, s35, 1
	v_readlane_b32 s7, v252, 25
	s_and_b64 s[6:7], s[6:7], exec
	s_cselect_b32 s6, s36, s35
	v_readlane_b32 s7, v252, 23
	s_mul_i32 s6, s6, s7
	v_readlane_b32 s7, v252, 21
	s_add_i32 s6, s6, s7
	s_ashr_i32 s7, s6, 31
	s_lshr_b32 s7, s7, 28
	s_add_i32 s7, s6, s7
	v_lshrrev_b32_e32 v5, 2, v3
	v_lshlrev_b32_e32 v6, 1, v3
	v_and_b32_e32 v2, 0xc0, v2
	s_ashr_i32 s8, s7, 4
	v_and_b32_e32 v5, 4, v5
	v_and_b32_e32 v6, 24, v6
	v_sub_u32_e32 v0, v0, v2
	s_lshl_b32 s9, s8, 3
	v_or3_b32 v4, v4, v5, v6
	v_lshlrev_b32_e32 v5, 5, v12
	v_ashrrev_i16_sdwa v0, v202, sext(v0) dst_sel:DWORD dst_unused:UNUSED_PAD src0_sel:DWORD src1_sel:BYTE_0
	s_sub_i32 s8, s33, s9
	v_and_b32_e32 v5, 32, v5
	v_bfe_i32 v15, v0, 0, 16
	s_min_u32 s11, s8, 8
	s_and_b32 s7, s7, -16
	v_add_lshl_u32 v2, v5, v15, 1
	s_sub_i32 s14, s6, s7
	v_cvt_f32_ubyte0_e32 v5, s11
	v_lshl_add_u32 v0, v4, 10, v2
	v_cvt_f32_i32_e32 v4, s14
	v_rcp_iflag_f32_e32 v6, v5
	v_lshl_add_u32 v134, v3, 10, v2
	s_ashr_i32 s6, s14, 30
	s_or_b32 s8, s6, 1
	v_mul_f32_e32 v2, v4, v6
	v_trunc_f32_e32 v2, v2
	v_fma_f32 v3, -v2, v5, v4
	v_cvt_i32_f32_e32 v2, v2
	v_cmp_ge_f32_e64 s[6:7], |v3|, v5
	s_and_b64 s[6:7], s[6:7], exec
	s_cselect_b32 s6, s8, 0
	v_readfirstlane_b32 s7, v2
	s_add_i32 s8, s7, s6
	s_mul_i32 s6, s8, s11
	s_sub_i32 s6, s14, s6
	s_sext_i32_i8 s6, s6
	s_add_i32 s22, s9, s6
	s_ashr_i32 s23, s22, 31
	s_lshl_b64 s[6:7], s[22:23], 18
	s_add_u32 s24, s4, s6
	s_addc_u32 s25, s5, s7
	s_bfe_i64 s[6:7], s[8:9], 0x80000
	s_lshl_b64 s[6:7], s[6:7], 18
	s_add_u32 s26, s30, s6
	s_addc_u32 s27, s31, s7
	s_add_i32 s23, s34, 0
	s_add_i32 m0, s23, 0x10000
	v_add_u32_e32 v136, 0x20000, v134
	global_load_lds_dwordx4 v0, s[26:27]
	s_add_i32 m0, s23, 0x12000
	s_add_u32 s6, s26, 0x20000
	global_load_lds_dwordx4 v130, s[26:27]
	s_addc_u32 s7, s27, 0
	s_add_i32 m0, s23, 0x14000
	s_add_i32 s37, s23, 0x2000
	global_load_lds_dwordx4 v0, s[6:7]
	s_add_i32 m0, s23, 0x16000
	s_add_i32 s38, s23, 0x4000
	global_load_lds_dwordx4 v130, s[6:7]
	s_mov_b32 m0, s23
	s_add_i32 s39, s23, 0x6000
	global_load_lds_dwordx4 v134, s[24:25]
	s_mov_b32 m0, s37
	v_add_u32_e32 v138, 0x20000, v132
	global_load_lds_dwordx4 v132, s[24:25]
	s_mov_b32 m0, s38
	v_mov_b32_e32 v131, v1
	global_load_lds_dwordx4 v136, s[24:25]
	s_mov_b32 m0, s39
	v_mov_b32_e32 v135, v1
	global_load_lds_dwordx4 v138, s[24:25]
	v_mov_b32_e32 v133, v1
	s_cmp_eq_u32 s13, 1
	v_lshl_add_u64 v[8:9], s[26:27], 0, v[0:1]
	v_lshl_add_u64 v[6:7], s[26:27], 0, v[130:131]
	v_lshl_add_u64 v[2:3], s[24:25], 0, v[134:135]
	s_cselect_b64 s[6:7], -1, 0
	s_cmp_lg_u32 s13, 1
	v_lshl_add_u64 v[4:5], s[24:25], 0, v[132:133]
	s_cbranch_scc1 .LBB0_1257
	s_barrier

; #define LAS __attribute__((address_space(3)))
; DEV void phase_prologue_a(const Frame& F0) {
;     ...
;         constexpr int D_ITEMS = (FF / 64) * 32;
;         for (int it = F.gw; it < NE * D_ITEMS; it += F.NGW) { const int e = it / D_ITEMS, r = it % D_ITEMS, kb = r / 32, nb = r % 32;
;             tr_item(GIN(I_WDOWN) + ((size_t)l * NE + e) * FF * 1024, 1024, 32 * nb, 64 * kb, (bf16_t*)(F.ws + WS_WD) + ((size_t)l * NE + e) * 1024 * FF, FF, 32 * nb, scr, F.lane); }
; DEV void phase_topk(const Frame& F0, int l) {
;     const Frame F = refresh(F0);
;     const int nitems = (l == DEPTH - 1) ? B_ * NE : 2 * B_ * NE;
;     LAS unsigned* hist = (LAS unsigned*)(F.lds);
;     LAS unsigned* selw = (LAS unsigned*)(F.lds + 1024);
;     LAS unsigned* cnt = (LAS unsigned*)(F.lds + 2048);
;     LAS int* selrow = (LAS int*)(F.lds + 8192);
;     const float* AFF = (const float*)(F.ws + WS_AFF); int* SLOT = (int*)(F.ws + WS_SLOT); float* EG = (float*)(F.ws + WS_EGATE);
;     for (int it = F.bid; it < nitems; it += F.G) {
.Lbw9_skip:
	s_waitcnt lgkmcnt(0)
	v_readlane_b32 s38, v255, 61
	s_cmp_lg_u32 s38, 0
	v_readlane_b32 s2, v253, 51
	v_readlane_b32 s3, v253, 52
	v_readlane_b32 s4, v251, 0
	s_and_b64 s[2:3], s[2:3], exec
	v_writelane_b32 v254, s58, 8
	v_readlane_b32 s5, v251, 1
	v_readlane_b32 s6, v251, 2
	v_readlane_b32 s7, v251, 3
	s_cselect_b32 s0, 64, 0x80
	v_writelane_b32 v254, s59, 9
	v_readlane_b32 s18, v251, 29
	v_mov_b32_e32 v0, v200
	s_mov_b64 s[4:5], s[6:7]
	s_cmp_ge_i32 s95, s0
	v_writelane_b32 v254, s57, 2
	v_writelane_b32 v253, s48, 49
	s_waitcnt lgkmcnt(0)
	s_barrier
	s_cbranch_scc0 .Ltk_busy
	v_readlane_b32 s2, v255, 51
	s_cmp_lg_u32 s2, 0x100
	s_cbranch_scc1 .LBB0_1705
	v_readlane_b32 s2, v255, 48
	s_cmp_lt_u32 s2, 0x80
	s_cbranch_scc1 .LBB0_1705
	v_readlane_b32 s36, v253, 62
	v_readlane_b32 s3, v251, 29
	s_sub_i32 s2, s2, 0x80
	s_lshl_b32 s2, s2, 3
	s_add_i32 s2, s2, s3
	v_readlane_b32 s6, v255, 53
	v_readlane_b32 s7, v255, 54
	s_cmp_lg_u32 s36, 0
	s_cbranch_scc1 .Ltk_gu
	v_readlane_b32 s4, v255, 49
	v_readlane_b32 s5, v255, 50
	s_add_u32 s6, s6, 0x22bc8000
	s_addc_u32 s7, s7, 0
	s_add_i32 s2, s2, 0x2700
	s_lshl_b32 s30, s3, 14
	v_and_b32_e32 v120, 31, v200
	v_lshlrev_b32_e32 v2, 2, v120
	v_lshrrev_b32_e32 v3, 5, v200
	v_and_b32_e32 v4, 7, v200
	v_lshrrev_b32_e32 v6, 3, v200
	v_mul_u32_u24_e32 v7, 33, v3
	v_add_u32_e32 v7, v7, v120
	v_lshl_add_u32 v7, v7, 2, s30
	v_add_u32_e32 v8, 0x400, v7
	v_add_u32_e32 v9, 0x840, v7
	v_add_u32_e32 v10, 0xc40, v7
	v_add_u32_e32 v11, 0x1080, v7
	v_add_u32_e32 v12, 0x1480, v7
	v_add_u32_e32 v13, 0x18c0, v7
	v_add_u32_e32 v14, 0x1cc0, v7
	v_mul_u32_u24_e32 v120, 0x108, v4
	v_add_u32_e32 v120, v120, v6
	v_lshl_add_u32 v15, v120, 2, s30
	v_lshl_add_u32 v122, v3, 12, v2
	v_mov_b32_e32 v123, 0
	v_lshlrev_b32_e32 v124, 4, v4
	v_lshl_add_u32 v124, v6, 12, v124
	v_mov_b32_e32 v125, 0
	s_mov_b64 s[40:41], 0x10000
	s_mov_b64 s[42:43], 0x8000
	s_mov_b64 s[44:45], 0x2000
.Ltk_dn_loop:
	s_lshr_b32 s8, s2, 10
	s_and_b32 s9, s2, 0x3ff
	s_lshr_b32 s10, s9, 5
	s_and_b32 s9, s9, 31
	s_lshl_b32 s24, s10, 18
	s_lshl_b32 s25, s9, 7
	s_add_i32 s24, s24, s25
	s_lshr_b32 s29, s8, 9
	s_lshl_b32 s28, s8, 23
	s_add_u32 s28, s28, s24
	s_addc_u32 s29, s29, 0
	s_add_u32 s28, s28, s4
	s_addc_u32 s29, s29, s5
	s_lshl_b32 s24, s9, 17
	s_lshl_b32 s25, s10, 7
	s_add_i32 s24, s24, s25
	s_lshr_b32 s11, s8, 10
	s_lshl_b32 s10, s8, 22
	s_add_u32 s10, s10, s24
	s_addc_u32 s11, s11, 0
	s_add_u32 s10, s10, s6
	s_addc_u32 s11, s11, s7
	v_lshl_add_u64 v[16:17], s[28:29], 0, v[122:123]
	v_lshl_add_u64 v[18:19], v[16:17], 0, s[44:45]
	v_lshl_add_u64 v[20:21], v[18:19], 0, s[44:45]
	v_lshl_add_u64 v[22:23], v[20:21], 0, s[44:45]
	v_lshl_add_u64 v[24:25], v[22:23], 0, s[44:45]
	v_lshl_add_u64 v[26:27], v[24:25], 0, s[44:45]
	v_lshl_add_u64 v[28:29], v[26:27], 0, s[44:45]
	v_lshl_add_u64 v[30:31], v[28:29], 0, s[44:45]
	global_load_dword v32, v[16:17], off nt
	global_load_dword v33, v[18:19], off nt
	global_load_dword v34, v[20:21], off nt
	global_load_dword v35, v[22:23], off nt
	global_load_dword v36, v[24:25], off nt
	global_load_dword v37, v[26:27], off nt
	global_load_dword v38, v[28:29], off nt
	global_load_dword v39, v[30:31], off nt
	v_lshl_add_u64 v[16:17], v[16:17], 0, s[40:41]
	v_lshl_add_u64 v[18:19], v[18:19], 0, s[40:41]
	v_lshl_add_u64 v[20:21], v[20:21], 0, s[40:41]
	v_lshl_add_u64 v[22:23], v[22:23], 0, s[40:41]
	v_lshl_add_u64 v[24:25], v[24:25], 0, s[40:41]
	v_lshl_add_u64 v[26:27], v[26:27], 0, s[40:41]
	v_lshl_add_u64 v[28:29], v[28:29], 0, s[40:41]
	v_lshl_add_u64 v[30:31], v[30:31], 0, s[40:41]
	global_load_dword v40, v[16:17], off nt
	global_load_dword v41, v[18:19], off nt
	global_load_dword v42, v[20:21], off nt
	global_load_dword v43, v[22:23], off nt
	global_load_dword v44, v[24:25], off nt
	global_load_dword v45, v[26:27], off nt
	global_load_dword v46, v[28:29], off nt
	global_load_dword v47, v[30:31], off nt
	v_lshl_add_u64 v[16:17], v[16:17], 0, s[40:41]
	v_lshl_add_u64 v[18:19], v[18:19], 0, s[40:41]
	v_lshl_add_u64 v[20:21], v[20:21], 0, s[40:41]
	v_lshl_add_u64 v[22:23], v[22:23], 0, s[40:41]
	v_lshl_add_u64 v[24:25], v[24:25], 0, s[40:41]
	v_lshl_add_u64 v[26:27], v[26:27], 0, s[40:41]
	v_lshl_add_u64 v[28:29], v[28:29], 0, s[40:41]
	v_lshl_add_u64 v[30:31], v[30:31], 0, s[40:41]
	global_load_dword v48, v[16:17], off nt
	global_load_dword v49, v[18:19], off nt
	global_load_dword v50, v[20:21], off nt
	global_load_dword v51, v[22:23], off nt
	global_load_dword v52, v[24:25], off nt
	global_load_dword v53, v[26:27], off nt
	global_load_dword v54, v[28:29], off nt
	global_load_dword v55, v[30:31], off nt
	v_lshl_add_u64 v[16:17], v[16:17], 0, s[40:41]
	v_lshl_add_u64 v[18:19], v[18:19], 0, s[40:41]
	v_lshl_add_u64 v[20:21], v[20:21], 0, s[40:41]
	v_lshl_add_u64 v[22:23], v[22:23], 0, s[40:41]
	v_lshl_add_u64 v[24:25], v[24:25], 0, s[40:41]
	v_lshl_add_u64 v[26:27], v[26:27], 0, s[40:41]
	v_lshl_add_u64 v[28:29], v[28:29], 0, s[40:41]
	v_lshl_add_u64 v[30:31], v[30:31], 0, s[40:41]
	global_load_dword v56, v[16:17], off nt
	global_load_dword v57, v[18:19], off nt
	global_load_dword v58, v[20:21], off nt
	global_load_dword v59, v[22:23], off nt
	global_load_dword v60, v[24:25], off nt
	global_load_dword v61, v[26:27], off nt
	global_load_dword v62, v[28:29], off nt
	global_load_dword v63, v[30:31], off nt
	v_lshl_add_u64 v[64:65], s[10:11], 0, v[124:125]
	v_lshl_add_u64 v[66:67], v[64:65], 0, s[42:43]
	v_lshl_add_u64 v[68:69], v[66:67], 0, s[42:43]
	v_lshl_add_u64 v[70:71], v[68:69], 0, s[42:43]
	s_add_i32 s31, s2, 0x400
	s_lshr_b32 s8, s31, 10
	s_and_b32 s9, s31, 0x3ff
	s_lshr_b32 s10, s9, 5
	s_and_b32 s9, s9, 31
; #define WAVE_LDS_SYNC() do { int _z = 0; (void)emu::wave_xchg(&_z, 4); } while (0)
; #define LAS __attribute__((address_space(3)))
; #define WAVE_LDS_SYNC() asm volatile("s_waitcnt lgkmcnt(0)" ::: "memory")
; #define NT_LOAD(p) __builtin_nontemporal_load(p)
; DEV void tr_item(const float* W, int ldw, int col0, int k0, bf16_t* WT, int K, int row0, LAS float* scr, int lane) {
; #pragma unroll 8
;     for (int i = 0; i < 32; ++i) { const int kk = 2 * i + (lane >> 5); scr[kk * 33 + (lane & 31)] = NT_LOAD(&W[(size_t)(k0 + kk) * ldw + col0 + (lane & 31)]); }
;     WAVE_LDS_SYNC();
;     const int c = lane & 7;
; #pragma unroll
;     for (int j = 0; j < 4; ++j) { const int n = (lane >> 3) + 8 * j; const LAS float* s = scr + (8 * c) * 33 + n;
	s_lshl_b32 s24, s10, 18
	s_lshl_b32 s25, s9, 7
	s_add_i32 s24, s24, s25
	s_lshr_b32 s29, s8, 9
	s_lshl_b32 s28, s8, 23
	s_add_u32 s28, s28, s24
	s_addc_u32 s29, s29, 0
	s_add_u32 s28, s28, s4
	s_addc_u32 s29, s29, s5
	s_lshl_b32 s24, s9, 17
	s_lshl_b32 s25, s10, 7
	s_add_i32 s24, s24, s25
	s_lshr_b32 s11, s8, 10
	s_lshl_b32 s10, s8, 22
	s_add_u32 s10, s10, s24
	s_addc_u32 s11, s11, 0
	s_add_u32 s10, s10, s6
	s_addc_u32 s11, s11, s7
	v_lshl_add_u64 v[16:17], s[28:29], 0, v[122:123]
	v_lshl_add_u64 v[18:19], v[16:17], 0, s[44:45]
	v_lshl_add_u64 v[20:21], v[18:19], 0, s[44:45]
	v_lshl_add_u64 v[22:23], v[20:21], 0, s[44:45]
	v_lshl_add_u64 v[24:25], v[22:23], 0, s[44:45]
	v_lshl_add_u64 v[26:27], v[24:25], 0, s[44:45]
	v_lshl_add_u64 v[28:29], v[26:27], 0, s[44:45]
	v_lshl_add_u64 v[30:31], v[28:29], 0, s[44:45]
	global_load_dword v162, v[16:17], off nt
	global_load_dword v163, v[18:19], off nt
	global_load_dword v164, v[20:21], off nt
	global_load_dword v165, v[22:23], off nt
	global_load_dword v166, v[24:25], off nt
	global_load_dword v167, v[26:27], off nt
	global_load_dword v168, v[28:29], off nt
	global_load_dword v169, v[30:31], off nt
	v_lshl_add_u64 v[16:17], v[16:17], 0, s[40:41]
	v_lshl_add_u64 v[18:19], v[18:19], 0, s[40:41]
	v_lshl_add_u64 v[20:21], v[20:21], 0, s[40:41]
	v_lshl_add_u64 v[22:23], v[22:23], 0, s[40:41]
	v_lshl_add_u64 v[24:25], v[24:25], 0, s[40:41]
	v_lshl_add_u64 v[26:27], v[26:27], 0, s[40:41]
	v_lshl_add_u64 v[28:29], v[28:29], 0, s[40:41]
	v_lshl_add_u64 v[30:31], v[30:31], 0, s[40:41]
	global_load_dword v170, v[16:17], off nt
	global_load_dword v171, v[18:19], off nt
	global_load_dword v172, v[20:21], off nt
	global_load_dword v173, v[22:23], off nt
	global_load_dword v174, v[24:25], off nt
	global_load_dword v175, v[26:27], off nt
	global_load_dword v176, v[28:29], off nt
	global_load_dword v177, v[30:31], off nt
	v_lshl_add_u64 v[16:17], v[16:17], 0, s[40:41]
	v_lshl_add_u64 v[18:19], v[18:19], 0, s[40:41]
	v_lshl_add_u64 v[20:21], v[20:21], 0, s[40:41]
	v_lshl_add_u64 v[22:23], v[22:23], 0, s[40:41]
	v_lshl_add_u64 v[24:25], v[24:25], 0, s[40:41]
	v_lshl_add_u64 v[26:27], v[26:27], 0, s[40:41]
	v_lshl_add_u64 v[28:29], v[28:29], 0, s[40:41]
	v_lshl_add_u64 v[30:31], v[30:31], 0, s[40:41]
	global_load_dword v178, v[16:17], off nt
	global_load_dword v179, v[18:19], off nt
	global_load_dword v180, v[20:21], off nt
	global_load_dword v181, v[22:23], off nt
	global_load_dword v182, v[24:25], off nt
	global_load_dword v183, v[26:27], off nt
	global_load_dword v184, v[28:29], off nt
	global_load_dword v185, v[30:31], off nt
	v_lshl_add_u64 v[16:17], v[16:17], 0, s[40:41]
	v_lshl_add_u64 v[18:19], v[18:19], 0, s[40:41]
	v_lshl_add_u64 v[20:21], v[20:21], 0, s[40:41]
	v_lshl_add_u64 v[22:23], v[22:23], 0, s[40:41]
	v_lshl_add_u64 v[24:25], v[24:25], 0, s[40:41]
	v_lshl_add_u64 v[26:27], v[26:27], 0, s[40:41]
	v_lshl_add_u64 v[28:29], v[28:29], 0, s[40:41]
	v_lshl_add_u64 v[30:31], v[30:31], 0, s[40:41]
	global_load_dword v186, v[16:17], off nt
	global_load_dword v187, v[18:19], off nt
	global_load_dword v188, v[20:21], off nt
	global_load_dword v189, v[22:23], off nt
	global_load_dword v190, v[24:25], off nt
	global_load_dword v191, v[26:27], off nt
	global_load_dword v192, v[28:29], off nt
	global_load_dword v193, v[30:31], off nt
	v_lshl_add_u64 v[126:127], s[10:11], 0, v[124:125]
	v_lshl_add_u64 v[128:129], v[126:127], 0, s[42:43]
	v_lshl_add_u64 v[130:131], v[128:129], 0, s[42:43]
	v_lshl_add_u64 v[132:133], v[130:131], 0, s[42:43]
	s_waitcnt vmcnt(62)
	ds_write2_b32 v7, v32, v33 offset1:66
	s_waitcnt vmcnt(60)
	ds_write2_b32 v7, v34, v35 offset0:132 offset1:198
	s_waitcnt vmcnt(58)
	ds_write2_b32 v8, v36, v37 offset0:8 offset1:74
	s_waitcnt vmcnt(56)
	ds_write2_b32 v8, v38, v39 offset0:140 offset1:206
	s_waitcnt vmcnt(54)
	ds_write2_b32 v9, v40, v41 offset1:66
	s_waitcnt vmcnt(52)
	ds_write2_b32 v9, v42, v43 offset0:132 offset1:198
	s_waitcnt vmcnt(50)
	ds_write2_b32 v10, v44, v45 offset0:8 offset1:74
	s_waitcnt vmcnt(48)
	ds_write2_b32 v10, v46, v47 offset0:140 offset1:206
	s_waitcnt vmcnt(46)
	ds_write2_b32 v11, v48, v49 offset1:66
	s_waitcnt vmcnt(44)
	ds_write2_b32 v11, v50, v51 offset0:132 offset1:198
	s_waitcnt vmcnt(42)
	ds_write2_b32 v12, v52, v53 offset0:8 offset1:74
	s_waitcnt vmcnt(40)
	ds_write2_b32 v12, v54, v55 offset0:140 offset1:206
	s_waitcnt vmcnt(38)
	ds_write2_b32 v13, v56, v57 offset1:66
	s_waitcnt vmcnt(36)
	ds_write2_b32 v13, v58, v59 offset0:132 offset1:198
	s_waitcnt vmcnt(34)
	ds_write2_b32 v14, v60, v61 offset0:8 offset1:74
	s_waitcnt vmcnt(32)
	ds_write2_b32 v14, v62, v63 offset0:140 offset1:206
	ds_read2_b32 v[72:73], v15 offset1:8
	ds_read2_b32 v[74:75], v15 offset0:33 offset1:41
	ds_read2_b32 v[76:77], v15 offset0:66 offset1:74
	ds_read2_b32 v[78:79], v15 offset0:99 offset1:107
	ds_read2_b32 v[80:81], v15 offset0:132 offset1:140
	ds_read2_b32 v[82:83], v15 offset0:165 offset1:173
	ds_read2_b32 v[84:85], v15 offset0:198 offset1:206
	ds_read2_b32 v[86:87], v15 offset0:231 offset1:239
	ds_read2_b32 v[88:89], v15 offset0:16 offset1:24
	ds_read2_b32 v[90:91], v15 offset0:49 offset1:57
	ds_read2_b32 v[92:93], v15 offset0:82 offset1:90
	ds_read2_b32 v[94:95], v15 offset0:115 offset1:123
	s_waitcnt lgkmcnt(4)
	v_cvt_pk_bf16_f32 v104, v72, v74
	v_cvt_pk_bf16_f32 v105, v76, v78
	v_cvt_pk_bf16_f32 v106, v80, v82
	v_cvt_pk_bf16_f32 v107, v84, v86
	v_cvt_pk_bf16_f32 v108, v73, v75
	v_cvt_pk_bf16_f32 v109, v77, v79
	v_cvt_pk_bf16_f32 v110, v81, v83
	v_cvt_pk_bf16_f32 v111, v85, v87
	ds_read2_b32 v[96:97], v15 offset0:148 offset1:156
	ds_read2_b32 v[98:99], v15 offset0:181 offset1:189
	ds_read2_b32 v[100:101], v15 offset0:214 offset1:222
	ds_read2_b32 v[102:103], v15 offset0:247 offset1:255
	global_store_dwordx4 v[64:65], v[104:107], off nt
	global_store_dwordx4 v[66:67], v[108:111], off nt
	s_waitcnt lgkmcnt(0)
; #define LAS __attribute__((address_space(3)))
; #define NT_STORE(v, p) __builtin_nontemporal_store((v), (p))
; DEV unsigned pk2(float lo, float hi) { return f2bf(lo) | (f2bf(hi) << 16); }
; DEV unsigned pk2(float lo, float hi) { const f32x2n_t v = {lo, hi}; return __builtin_bit_cast(unsigned, __builtin_convertvector(v, bf16x2n_t)); }
; DEV void tr_item(const float* W, int ldw, int col0, int k0, bf16_t* WT, int K, int row0, LAS float* scr, int lane) {
;     ...
; #pragma unroll
;     for (int j = 0; j < 4; ++j) { const int n = (lane >> 3) + 8 * j; const LAS float* s = scr + (8 * c) * 33 + n;
;         u32x4 o; o.x = pk2(s[0 * 33], s[1 * 33]); o.y = pk2(s[2 * 33], s[3 * 33]); o.z = pk2(s[4 * 33], s[5 * 33]); o.w = pk2(s[6 * 33], s[7 * 33]);
;         NT_STORE(o, (u32x4*)(WT + (size_t)(row0 + n) * K + k0 + 8 * c)); }
; DEV void phase_prologue_a(const Frame& F0) {
;     ...
;         constexpr int GU_NB = 2 * FF / 32, GU_ITEMS = 16 * GU_NB;
;         for (int it = F.gw; it < NE * GU_ITEMS; it += F.NGW) { const int e = it / GU_ITEMS, r = it % GU_ITEMS, kb = r / GU_NB, nb = r % GU_NB; const int d0 = 32 * nb, j = d0 >> 8, w = d0 & 255;
;             const float* src = (w < 128 ? GIN(I_WGATE) : GIN(I_WUP)) + ((size_t)l * NE + e) * 1024 * FF;
;             tr_item(src, FF, 128 * j + (w & 127), 64 * kb, (bf16_t*)(F.ws + WS_WGU) + ((size_t)l * NE + e) * 2 * FF * 1024, 1024, d0, scr, F.lane); }
	v_cvt_pk_bf16_f32 v112, v88, v90
	v_cvt_pk_bf16_f32 v113, v92, v94
	v_cvt_pk_bf16_f32 v114, v96, v98
	v_cvt_pk_bf16_f32 v115, v100, v102
	v_cvt_pk_bf16_f32 v116, v89, v91
	v_cvt_pk_bf16_f32 v117, v93, v95
	v_cvt_pk_bf16_f32 v118, v97, v99
	v_cvt_pk_bf16_f32 v119, v101, v103
	global_store_dwordx4 v[68:69], v[112:115], off nt
	global_store_dwordx4 v[70:71], v[116:119], off nt
	s_waitcnt vmcnt(34)
	ds_write2_b32 v7, v162, v163 offset1:66
	s_waitcnt vmcnt(32)
	ds_write2_b32 v7, v164, v165 offset0:132 offset1:198
	s_waitcnt vmcnt(30)
	ds_write2_b32 v8, v166, v167 offset0:8 offset1:74
	s_waitcnt vmcnt(28)
	ds_write2_b32 v8, v168, v169 offset0:140 offset1:206
	s_waitcnt vmcnt(26)
	ds_write2_b32 v9, v170, v171 offset1:66
	s_waitcnt vmcnt(24)
	ds_write2_b32 v9, v172, v173 offset0:132 offset1:198
	s_waitcnt vmcnt(22)
	ds_write2_b32 v10, v174, v175 offset0:8 offset1:74
	s_waitcnt vmcnt(20)
	ds_write2_b32 v10, v176, v177 offset0:140 offset1:206
	s_waitcnt vmcnt(18)
	ds_write2_b32 v11, v178, v179 offset1:66
	s_waitcnt vmcnt(16)
	ds_write2_b32 v11, v180, v181 offset0:132 offset1:198
	s_waitcnt vmcnt(14)
	ds_write2_b32 v12, v182, v183 offset0:8 offset1:74
	s_waitcnt vmcnt(12)
	ds_write2_b32 v12, v184, v185 offset0:140 offset1:206
	s_waitcnt vmcnt(10)
	ds_write2_b32 v13, v186, v187 offset1:66
	s_waitcnt vmcnt(8)
	ds_write2_b32 v13, v188, v189 offset0:132 offset1:198
	s_waitcnt vmcnt(6)
	ds_write2_b32 v14, v190, v191 offset0:8 offset1:74
	s_waitcnt vmcnt(4)
	ds_write2_b32 v14, v192, v193 offset0:140 offset1:206
	ds_read2_b32 v[72:73], v15 offset1:8
	ds_read2_b32 v[74:75], v15 offset0:33 offset1:41
	ds_read2_b32 v[76:77], v15 offset0:66 offset1:74
	ds_read2_b32 v[78:79], v15 offset0:99 offset1:107
	ds_read2_b32 v[80:81], v15 offset0:132 offset1:140
	ds_read2_b32 v[82:83], v15 offset0:165 offset1:173
	ds_read2_b32 v[84:85], v15 offset0:198 offset1:206
	ds_read2_b32 v[86:87], v15 offset0:231 offset1:239
	ds_read2_b32 v[88:89], v15 offset0:16 offset1:24
	ds_read2_b32 v[90:91], v15 offset0:49 offset1:57
	ds_read2_b32 v[92:93], v15 offset0:82 offset1:90
	ds_read2_b32 v[94:95], v15 offset0:115 offset1:123
	s_waitcnt lgkmcnt(4)
	v_cvt_pk_bf16_f32 v104, v72, v74
	v_cvt_pk_bf16_f32 v105, v76, v78
	v_cvt_pk_bf16_f32 v106, v80, v82
	v_cvt_pk_bf16_f32 v107, v84, v86
	v_cvt_pk_bf16_f32 v108, v73, v75
	v_cvt_pk_bf16_f32 v109, v77, v79
	v_cvt_pk_bf16_f32 v110, v81, v83
	v_cvt_pk_bf16_f32 v111, v85, v87
	ds_read2_b32 v[96:97], v15 offset0:148 offset1:156
	ds_read2_b32 v[98:99], v15 offset0:181 offset1:189
	ds_read2_b32 v[100:101], v15 offset0:214 offset1:222
	ds_read2_b32 v[102:103], v15 offset0:247 offset1:255
	global_store_dwordx4 v[126:127], v[104:107], off nt
	global_store_dwordx4 v[128:129], v[108:111], off nt
	s_waitcnt lgkmcnt(0)
	v_cvt_pk_bf16_f32 v112, v88, v90
	v_cvt_pk_bf16_f32 v113, v92, v94
	v_cvt_pk_bf16_f32 v114, v96, v98
	v_cvt_pk_bf16_f32 v115, v100, v102
	v_cvt_pk_bf16_f32 v116, v89, v91
	v_cvt_pk_bf16_f32 v117, v93, v95
	v_cvt_pk_bf16_f32 v118, v97, v99
	v_cvt_pk_bf16_f32 v119, v101, v103
	global_store_dwordx4 v[130:131], v[112:115], off nt
	global_store_dwordx4 v[132:133], v[116:119], off nt
	s_add_i32 s2, s2, 0x800
	s_cmp_lt_u32 s2, 0x3700
	s_cbranch_scc1 .Ltk_dn_loop
	s_branch .LBB0_1705
.Ltk_gu:
	v_readlane_b32 s4, v255, 55
	v_readlane_b32 s5, v255, 56
	v_readlane_b32 s34, v255, 57
	v_readlane_b32 s35, v255, 58
	s_add_u32 s6, s6, 0x2bc8000
	s_addc_u32 s7, s7, 0
	s_mov_b32 s8, 0x10000000
	s_mov_b32 s37, 0x1b00
	s_cmp_eq_u32 s36, 1
	s_cbranch_scc1 .Ltk_go
	s_mov_b32 s8, 0x18000000
	s_mov_b32 s37, 0x1e00
	s_cmp_eq_u32 s36, 2
	s_cbranch_scc1 .Ltk_go
	s_mov_b32 s37, 0x2e00
.Ltk_go:
	s_add_u32 s4, s4, s8
	s_addc_u32 s5, s5, 0
	s_add_u32 s34, s34, s8
	s_addc_u32 s35, s35, 0
	s_add_u32 s6, s6, s8
	s_addc_u32 s7, s7, 0
	s_add_i32 s2, s2, s37
	s_add_i32 s101, s37, 0x1000
	s_lshl_b32 s30, s3, 14
	v_and_b32_e32 v120, 31, v200
	v_lshlrev_b32_e32 v2, 2, v120
	v_lshrrev_b32_e32 v3, 5, v200
	v_and_b32_e32 v4, 7, v200
	v_lshrrev_b32_e32 v6, 3, v200
	v_mul_u32_u24_e32 v7, 33, v3
	v_add_u32_e32 v7, v7, v120
	v_lshl_add_u32 v7, v7, 2, s30
	v_add_u32_e32 v8, 0x400, v7
	v_add_u32_e32 v9, 0x840, v7
	v_add_u32_e32 v10, 0xc40, v7
	v_add_u32_e32 v11, 0x1080, v7
	v_add_u32_e32 v12, 0x1480, v7
	v_add_u32_e32 v13, 0x18c0, v7
	v_add_u32_e32 v14, 0x1cc0, v7
	v_mul_u32_u24_e32 v120, 0x108, v4
	v_add_u32_e32 v120, v120, v6
	v_lshl_add_u32 v15, v120, 2, s30
	v_lshl_add_u32 v122, v3, 13, v2
	v_mov_b32_e32 v123, 0
	v_lshlrev_b32_e32 v124, 4, v4
	v_lshl_add_u32 v124, v6, 11, v124
	v_mov_b32_e32 v125, 0
	s_mov_b64 s[40:41], 0x20000
	s_mov_b64 s[42:43], 0x4000
	s_mov_b64 s[44:45], 0x4000
; #define LAS __attribute__((address_space(3)))
; #define NT_LOAD(p) __builtin_nontemporal_load(p)
; DEV void tr_item(const float* W, int ldw, int col0, int k0, bf16_t* WT, int K, int row0, LAS float* scr, int lane) {
; #pragma unroll 8
;     for (int i = 0; i < 32; ++i) { const int kk = 2 * i + (lane >> 5); scr[kk * 33 + (lane & 31)] = NT_LOAD(&W[(size_t)(k0 + kk) * ldw + col0 + (lane & 31)]); }
; DEV void phase_prologue_a(const Frame& F0) {
;     ...
;         constexpr int GU_NB = 2 * FF / 32, GU_ITEMS = 16 * GU_NB;
;         for (int it = F.gw; it < NE * GU_ITEMS; it += F.NGW) { const int e = it / GU_ITEMS, r = it % GU_ITEMS, kb = r / GU_NB, nb = r % GU_NB; const int d0 = 32 * nb, j = d0 >> 8, w = d0 & 255;
;             const float* src = (w < 128 ? GIN(I_WGATE) : GIN(I_WUP)) + ((size_t)l * NE + e) * 1024 * FF;
;             tr_item(src, FF, 128 * j + (w & 127), 64 * kb, (bf16_t*)(F.ws + WS_WGU) + ((size_t)l * NE + e) * 2 * FF * 1024, 1024, d0, scr, F.lane); }
.Ltk_gu_loop:
	s_lshr_b32 s8, s2, 11
	s_and_b32 s9, s2, 0x7ff
	s_lshr_b32 s10, s9, 7
	s_and_b32 s9, s9, 0x7f
	s_lshl_b32 s24, s10, 19
	s_lshr_b32 s25, s9, 3
	s_lshl_b32 s25, s25, 9
	s_add_i32 s24, s24, s25
	s_and_b32 s25, s9, 3
	s_lshl_b32 s25, s25, 7
	s_add_i32 s24, s24, s25
	s_lshr_b32 s29, s8, 9
	s_lshl_b32 s28, s8, 23
	s_add_u32 s28, s28, s24
	s_addc_u32 s29, s29, 0
	s_bitcmp0_b32 s9, 2
	s_cselect_b32 s24, s4, s34
	s_cselect_b32 s25, s5, s35
	s_add_u32 s28, s28, s24
	s_addc_u32 s29, s29, s25
	s_lshl_b32 s24, s9, 16
	s_lshl_b32 s25, s10, 7
	s_add_i32 s24, s24, s25
	s_lshr_b32 s11, s8, 9
	s_lshl_b32 s10, s8, 23
	s_add_u32 s10, s10, s24
	s_addc_u32 s11, s11, 0
	s_add_u32 s10, s10, s6
	s_addc_u32 s11, s11, s7
	v_lshl_add_u64 v[16:17], s[28:29], 0, v[122:123]
	v_lshl_add_u64 v[18:19], v[16:17], 0, s[44:45]
	v_lshl_add_u64 v[20:21], v[18:19], 0, s[44:45]
	v_lshl_add_u64 v[22:23], v[20:21], 0, s[44:45]
	v_lshl_add_u64 v[24:25], v[22:23], 0, s[44:45]
	v_lshl_add_u64 v[26:27], v[24:25], 0, s[44:45]
	v_lshl_add_u64 v[28:29], v[26:27], 0, s[44:45]
	v_lshl_add_u64 v[30:31], v[28:29], 0, s[44:45]
	global_load_dword v32, v[16:17], off nt
	global_load_dword v33, v[18:19], off nt
	global_load_dword v34, v[20:21], off nt
	global_load_dword v35, v[22:23], off nt
	global_load_dword v36, v[24:25], off nt
	global_load_dword v37, v[26:27], off nt
	global_load_dword v38, v[28:29], off nt
	global_load_dword v39, v[30:31], off nt
	v_lshl_add_u64 v[16:17], v[16:17], 0, s[40:41]
	v_lshl_add_u64 v[18:19], v[18:19], 0, s[40:41]
	v_lshl_add_u64 v[20:21], v[20:21], 0, s[40:41]
	v_lshl_add_u64 v[22:23], v[22:23], 0, s[40:41]
	v_lshl_add_u64 v[24:25], v[24:25], 0, s[40:41]
	v_lshl_add_u64 v[26:27], v[26:27], 0, s[40:41]
	v_lshl_add_u64 v[28:29], v[28:29], 0, s[40:41]
	v_lshl_add_u64 v[30:31], v[30:31], 0, s[40:41]
	global_load_dword v40, v[16:17], off nt
	global_load_dword v41, v[18:19], off nt
	global_load_dword v42, v[20:21], off nt
	global_load_dword v43, v[22:23], off nt
	global_load_dword v44, v[24:25], off nt
	global_load_dword v45, v[26:27], off nt
	global_load_dword v46, v[28:29], off nt
	global_load_dword v47, v[30:31], off nt
	v_lshl_add_u64 v[16:17], v[16:17], 0, s[40:41]
	v_lshl_add_u64 v[18:19], v[18:19], 0, s[40:41]
	v_lshl_add_u64 v[20:21], v[20:21], 0, s[40:41]
	v_lshl_add_u64 v[22:23], v[22:23], 0, s[40:41]
	v_lshl_add_u64 v[24:25], v[24:25], 0, s[40:41]
	v_lshl_add_u64 v[26:27], v[26:27], 0, s[40:41]
	v_lshl_add_u64 v[28:29], v[28:29], 0, s[40:41]
	v_lshl_add_u64 v[30:31], v[30:31], 0, s[40:41]
	global_load_dword v48, v[16:17], off nt
	global_load_dword v49, v[18:19], off nt
	global_load_dword v50, v[20:21], off nt
	global_load_dword v51, v[22:23], off nt
	global_load_dword v52, v[24:25], off nt
	global_load_dword v53, v[26:27], off nt
	global_load_dword v54, v[28:29], off nt
	global_load_dword v55, v[30:31], off nt
	v_lshl_add_u64 v[16:17], v[16:17], 0, s[40:41]
	v_lshl_add_u64 v[18:19], v[18:19], 0, s[40:41]
	v_lshl_add_u64 v[20:21], v[20:21], 0, s[40:41]
	v_lshl_add_u64 v[22:23], v[22:23], 0, s[40:41]
	v_lshl_add_u64 v[24:25], v[24:25], 0, s[40:41]
	v_lshl_add_u64 v[26:27], v[26:27], 0, s[40:41]
	v_lshl_add_u64 v[28:29], v[28:29], 0, s[40:41]
	v_lshl_add_u64 v[30:31], v[30:31], 0, s[40:41]
	global_load_dword v56, v[16:17], off nt
	global_load_dword v57, v[18:19], off nt
	global_load_dword v58, v[20:21], off nt
	global_load_dword v59, v[22:23], off nt
	global_load_dword v60, v[24:25], off nt
	global_load_dword v61, v[26:27], off nt
	global_load_dword v62, v[28:29], off nt
	global_load_dword v63, v[30:31], off nt
	v_lshl_add_u64 v[64:65], s[10:11], 0, v[124:125]
	v_lshl_add_u64 v[66:67], v[64:65], 0, s[42:43]
	v_lshl_add_u64 v[68:69], v[66:67], 0, s[42:43]
	v_lshl_add_u64 v[70:71], v[68:69], 0, s[42:43]
	s_add_i32 s31, s2, 0x400
	s_lshr_b32 s8, s31, 11
	s_and_b32 s9, s31, 0x7ff
	s_lshr_b32 s10, s9, 7
	s_and_b32 s9, s9, 0x7f
	s_lshl_b32 s24, s10, 19
	s_lshr_b32 s25, s9, 3
	s_lshl_b32 s25, s25, 9
	s_add_i32 s24, s24, s25
	s_and_b32 s25, s9, 3
	s_lshl_b32 s25, s25, 7
	s_add_i32 s24, s24, s25
	s_lshr_b32 s29, s8, 9
	s_lshl_b32 s28, s8, 23
	s_add_u32 s28, s28, s24
	s_addc_u32 s29, s29, 0
	s_bitcmp0_b32 s9, 2
	s_cselect_b32 s24, s4, s34
	s_cselect_b32 s25, s5, s35
	s_add_u32 s28, s28, s24
	s_addc_u32 s29, s29, s25
	s_lshl_b32 s24, s9, 16
	s_lshl_b32 s25, s10, 7
	s_add_i32 s24, s24, s25
	s_lshr_b32 s11, s8, 9
	s_lshl_b32 s10, s8, 23
	s_add_u32 s10, s10, s24
	s_addc_u32 s11, s11, 0
	s_add_u32 s10, s10, s6
	s_addc_u32 s11, s11, s7
	v_lshl_add_u64 v[16:17], s[28:29], 0, v[122:123]
	v_lshl_add_u64 v[18:19], v[16:17], 0, s[44:45]
	v_lshl_add_u64 v[20:21], v[18:19], 0, s[44:45]
	v_lshl_add_u64 v[22:23], v[20:21], 0, s[44:45]
	v_lshl_add_u64 v[24:25], v[22:23], 0, s[44:45]
	v_lshl_add_u64 v[26:27], v[24:25], 0, s[44:45]
	v_lshl_add_u64 v[28:29], v[26:27], 0, s[44:45]
	v_lshl_add_u64 v[30:31], v[28:29], 0, s[44:45]
	global_load_dword v162, v[16:17], off nt
	global_load_dword v163, v[18:19], off nt
	global_load_dword v164, v[20:21], off nt
	global_load_dword v165, v[22:23], off nt
	global_load_dword v166, v[24:25], off nt
	global_load_dword v167, v[26:27], off nt
	global_load_dword v168, v[28:29], off nt
	global_load_dword v169, v[30:31], off nt
	v_lshl_add_u64 v[16:17], v[16:17], 0, s[40:41]
	v_lshl_add_u64 v[18:19], v[18:19], 0, s[40:41]
	v_lshl_add_u64 v[20:21], v[20:21], 0, s[40:41]
	v_lshl_add_u64 v[22:23], v[22:23], 0, s[40:41]
	v_lshl_add_u64 v[24:25], v[24:25], 0, s[40:41]
	v_lshl_add_u64 v[26:27], v[26:27], 0, s[40:41]
	v_lshl_add_u64 v[28:29], v[28:29], 0, s[40:41]
	v_lshl_add_u64 v[30:31], v[30:31], 0, s[40:41]
	global_load_dword v170, v[16:17], off nt
; #define WAVE_LDS_SYNC() do { int _z = 0; (void)emu::wave_xchg(&_z, 4); } while (0)
; #define LAS __attribute__((address_space(3)))
; #define WAVE_LDS_SYNC() asm volatile("s_waitcnt lgkmcnt(0)" ::: "memory")
; #define NT_LOAD(p) __builtin_nontemporal_load(p)
; DEV void tr_item(const float* W, int ldw, int col0, int k0, bf16_t* WT, int K, int row0, LAS float* scr, int lane) {
; #pragma unroll 8
;     for (int i = 0; i < 32; ++i) { const int kk = 2 * i + (lane >> 5); scr[kk * 33 + (lane & 31)] = NT_LOAD(&W[(size_t)(k0 + kk) * ldw + col0 + (lane & 31)]); }
;     WAVE_LDS_SYNC();
;     const int c = lane & 7;
; #pragma unroll
;     for (int j = 0; j < 4; ++j) { const int n = (lane >> 3) + 8 * j; const LAS float* s = scr + (8 * c) * 33 + n;
	global_load_dword v171, v[18:19], off nt
	global_load_dword v172, v[20:21], off nt
	global_load_dword v173, v[22:23], off nt
	global_load_dword v174, v[24:25], off nt
	global_load_dword v175, v[26:27], off nt
	global_load_dword v176, v[28:29], off nt
	global_load_dword v177, v[30:31], off nt
	v_lshl_add_u64 v[16:17], v[16:17], 0, s[40:41]
	v_lshl_add_u64 v[18:19], v[18:19], 0, s[40:41]
	v_lshl_add_u64 v[20:21], v[20:21], 0, s[40:41]
	v_lshl_add_u64 v[22:23], v[22:23], 0, s[40:41]
	v_lshl_add_u64 v[24:25], v[24:25], 0, s[40:41]
	v_lshl_add_u64 v[26:27], v[26:27], 0, s[40:41]
	v_lshl_add_u64 v[28:29], v[28:29], 0, s[40:41]
	v_lshl_add_u64 v[30:31], v[30:31], 0, s[40:41]
	global_load_dword v178, v[16:17], off nt
	global_load_dword v179, v[18:19], off nt
	global_load_dword v180, v[20:21], off nt
	global_load_dword v181, v[22:23], off nt
	global_load_dword v182, v[24:25], off nt
	global_load_dword v183, v[26:27], off nt
	global_load_dword v184, v[28:29], off nt
	global_load_dword v185, v[30:31], off nt
	v_lshl_add_u64 v[16:17], v[16:17], 0, s[40:41]
	v_lshl_add_u64 v[18:19], v[18:19], 0, s[40:41]
	v_lshl_add_u64 v[20:21], v[20:21], 0, s[40:41]
	v_lshl_add_u64 v[22:23], v[22:23], 0, s[40:41]
	v_lshl_add_u64 v[24:25], v[24:25], 0, s[40:41]
	v_lshl_add_u64 v[26:27], v[26:27], 0, s[40:41]
	v_lshl_add_u64 v[28:29], v[28:29], 0, s[40:41]
	v_lshl_add_u64 v[30:31], v[30:31], 0, s[40:41]
	global_load_dword v186, v[16:17], off nt
	global_load_dword v187, v[18:19], off nt
	global_load_dword v188, v[20:21], off nt
	global_load_dword v189, v[22:23], off nt
	global_load_dword v190, v[24:25], off nt
	global_load_dword v191, v[26:27], off nt
	global_load_dword v192, v[28:29], off nt
	global_load_dword v193, v[30:31], off nt
	v_lshl_add_u64 v[126:127], s[10:11], 0, v[124:125]
	v_lshl_add_u64 v[128:129], v[126:127], 0, s[42:43]
	v_lshl_add_u64 v[130:131], v[128:129], 0, s[42:43]
	v_lshl_add_u64 v[132:133], v[130:131], 0, s[42:43]
	s_waitcnt vmcnt(62)
	ds_write2_b32 v7, v32, v33 offset1:66
	s_waitcnt vmcnt(60)
	ds_write2_b32 v7, v34, v35 offset0:132 offset1:198
	s_waitcnt vmcnt(58)
	ds_write2_b32 v8, v36, v37 offset0:8 offset1:74
	s_waitcnt vmcnt(56)
	ds_write2_b32 v8, v38, v39 offset0:140 offset1:206
	s_waitcnt vmcnt(54)
	ds_write2_b32 v9, v40, v41 offset1:66
	s_waitcnt vmcnt(52)
	ds_write2_b32 v9, v42, v43 offset0:132 offset1:198
	s_waitcnt vmcnt(50)
	ds_write2_b32 v10, v44, v45 offset0:8 offset1:74
	s_waitcnt vmcnt(48)
	ds_write2_b32 v10, v46, v47 offset0:140 offset1:206
	s_waitcnt vmcnt(46)
	ds_write2_b32 v11, v48, v49 offset1:66
	s_waitcnt vmcnt(44)
	ds_write2_b32 v11, v50, v51 offset0:132 offset1:198
	s_waitcnt vmcnt(42)
	ds_write2_b32 v12, v52, v53 offset0:8 offset1:74
	s_waitcnt vmcnt(40)
	ds_write2_b32 v12, v54, v55 offset0:140 offset1:206
	s_waitcnt vmcnt(38)
	ds_write2_b32 v13, v56, v57 offset1:66
	s_waitcnt vmcnt(36)
	ds_write2_b32 v13, v58, v59 offset0:132 offset1:198
	s_waitcnt vmcnt(34)
	ds_write2_b32 v14, v60, v61 offset0:8 offset1:74
	s_waitcnt vmcnt(32)
	ds_write2_b32 v14, v62, v63 offset0:140 offset1:206
	ds_read2_b32 v[72:73], v15 offset1:8
	ds_read2_b32 v[74:75], v15 offset0:33 offset1:41
	ds_read2_b32 v[76:77], v15 offset0:66 offset1:74
	ds_read2_b32 v[78:79], v15 offset0:99 offset1:107
	ds_read2_b32 v[80:81], v15 offset0:132 offset1:140
	ds_read2_b32 v[82:83], v15 offset0:165 offset1:173
	ds_read2_b32 v[84:85], v15 offset0:198 offset1:206
	ds_read2_b32 v[86:87], v15 offset0:231 offset1:239
	ds_read2_b32 v[88:89], v15 offset0:16 offset1:24
	ds_read2_b32 v[90:91], v15 offset0:49 offset1:57
	ds_read2_b32 v[92:93], v15 offset0:82 offset1:90
	ds_read2_b32 v[94:95], v15 offset0:115 offset1:123
	s_waitcnt lgkmcnt(4)
	v_cvt_pk_bf16_f32 v104, v72, v74
	v_cvt_pk_bf16_f32 v105, v76, v78
	v_cvt_pk_bf16_f32 v106, v80, v82
	v_cvt_pk_bf16_f32 v107, v84, v86
	v_cvt_pk_bf16_f32 v108, v73, v75
	v_cvt_pk_bf16_f32 v109, v77, v79
	v_cvt_pk_bf16_f32 v110, v81, v83
	v_cvt_pk_bf16_f32 v111, v85, v87
	ds_read2_b32 v[96:97], v15 offset0:148 offset1:156
	ds_read2_b32 v[98:99], v15 offset0:181 offset1:189
	ds_read2_b32 v[100:101], v15 offset0:214 offset1:222
	ds_read2_b32 v[102:103], v15 offset0:247 offset1:255
	global_store_dwordx4 v[64:65], v[104:107], off nt
	global_store_dwordx4 v[66:67], v[108:111], off nt
	s_waitcnt lgkmcnt(0)
	v_cvt_pk_bf16_f32 v112, v88, v90
	v_cvt_pk_bf16_f32 v113, v92, v94
	v_cvt_pk_bf16_f32 v114, v96, v98
	v_cvt_pk_bf16_f32 v115, v100, v102
	v_cvt_pk_bf16_f32 v116, v89, v91
	v_cvt_pk_bf16_f32 v117, v93, v95
	v_cvt_pk_bf16_f32 v118, v97, v99
	v_cvt_pk_bf16_f32 v119, v101, v103
	global_store_dwordx4 v[68:69], v[112:115], off nt
	global_store_dwordx4 v[70:71], v[116:119], off nt
	s_waitcnt vmcnt(34)
	ds_write2_b32 v7, v162, v163 offset1:66
	s_waitcnt vmcnt(32)
	ds_write2_b32 v7, v164, v165 offset0:132 offset1:198
	s_waitcnt vmcnt(30)
	ds_write2_b32 v8, v166, v167 offset0:8 offset1:74
	s_waitcnt vmcnt(28)
	ds_write2_b32 v8, v168, v169 offset0:140 offset1:206
	s_waitcnt vmcnt(26)
	ds_write2_b32 v9, v170, v171 offset1:66
	s_waitcnt vmcnt(24)
	ds_write2_b32 v9, v172, v173 offset0:132 offset1:198
	s_waitcnt vmcnt(22)
	ds_write2_b32 v10, v174, v175 offset0:8 offset1:74
	s_waitcnt vmcnt(20)
	ds_write2_b32 v10, v176, v177 offset0:140 offset1:206
	s_waitcnt vmcnt(18)
	ds_write2_b32 v11, v178, v179 offset1:66
	s_waitcnt vmcnt(16)
	ds_write2_b32 v11, v180, v181 offset0:132 offset1:198
	s_waitcnt vmcnt(14)
	ds_write2_b32 v12, v182, v183 offset0:8 offset1:74
	s_waitcnt vmcnt(12)
	ds_write2_b32 v12, v184, v185 offset0:140 offset1:206
	s_waitcnt vmcnt(10)
	ds_write2_b32 v13, v186, v187 offset1:66
	s_waitcnt vmcnt(8)
; DEV void tr_item(const float* W, int ldw, int col0, int k0, bf16_t* WT, int K, int row0, LAS float* scr, int lane) {
;     ...
; #pragma unroll
;     for (int j = 0; j < 4; ++j) { const int n = (lane >> 3) + 8 * j; const LAS float* s = scr + (8 * c) * 33 + n;
;         u32x4 o; o.x = pk2(s[0 * 33], s[1 * 33]); o.y = pk2(s[2 * 33], s[3 * 33]); o.z = pk2(s[4 * 33], s[5 * 33]); o.w = pk2(s[6 * 33], s[7 * 33]);
;         NT_STORE(o, (u32x4*)(WT + (size_t)(row0 + n) * K + k0 + 8 * c)); }
; DEV void phase_topk(const Frame& F0, int l) {
;     ...
;     for (int it = F.bid; it < nitems; it += F.G) {
;         const int e = it % NE, set = it / NE, kind = set / B_, b = set % B_;
;         const int n = kind ? CTX : SEQ, cap = kind ? CAPC : CAPL; const int row0 = kind ? LATR + b * CTX : b * SEQ;
;         const int sbase = kind ? B_ * CAPL + b * CAPC : b * CAPL;
;         const int per = n >= NTHREADS ? n / NTHREADS : 1; const bool act = F.tid * per < n;
;         unsigned key[8];
; #pragma unroll
;         for (int k = 0; k < 8; ++k) key[k] = (act && k < per) ? __builtin_bit_cast(unsigned, AFF[(size_t)(row0 + F.tid * per + k) * 16 + e]) : 0u;
;         unsigned prefix = 0u, remaining = (unsigned)cap;
;         for (int pass = 0; pass < 4; ++pass) {
;             const int shift = 24 - 8 * pass; const unsigned mask = pass == 0 ? 0u : (0xFFFFFFFFu << (shift + 8));
;             if (F.tid < 256) hist[F.tid] = 0u;
;             __syncthreads();
; #pragma unroll
;             for (int k = 0; k < 8; ++k) if (act && k < per && ((key[k] & mask) == (prefix & mask))) lds_atomic_add(&hist[(key[k] >> shift) & 255u], 1u);
;             __syncthreads();
;             if (F.wave == 0) {
;                 const unsigned h0 = hist[4 * F.lane], h1 = hist[4 * F.lane + 1], h2 = hist[4 * F.lane + 2], h3 = hist[4 * F.lane + 3];
;                 unsigned suf = h0 + h1 + h2 + h3;
; #pragma unroll
;                 for (int o = 1; o < 64; o <<= 1) { const unsigned tv = shfl_t(suf, F.lane + o); if (F.lane + o < 64) suf += tv; }
;                 unsigned cum = suf - (h0 + h1 + h2 + h3);
;                 int dsel = -1; unsigned above = 0u;
;                 if (cum < remaining) {
;                     if (cum + h3 >= remaining) { dsel = 4 * F.lane + 3; above = cum; }
;                     else if (cum + h3 + h2 >= remaining) { dsel = 4 * F.lane + 2; above = cum + h3; }
	ds_write2_b32 v13, v188, v189 offset0:132 offset1:198
	s_waitcnt vmcnt(6)
	ds_write2_b32 v14, v190, v191 offset0:8 offset1:74
	s_waitcnt vmcnt(4)
	ds_write2_b32 v14, v192, v193 offset0:140 offset1:206
	ds_read2_b32 v[72:73], v15 offset1:8
	ds_read2_b32 v[74:75], v15 offset0:33 offset1:41
	ds_read2_b32 v[76:77], v15 offset0:66 offset1:74
	ds_read2_b32 v[78:79], v15 offset0:99 offset1:107
	ds_read2_b32 v[80:81], v15 offset0:132 offset1:140
	ds_read2_b32 v[82:83], v15 offset0:165 offset1:173
	ds_read2_b32 v[84:85], v15 offset0:198 offset1:206
	ds_read2_b32 v[86:87], v15 offset0:231 offset1:239
	ds_read2_b32 v[88:89], v15 offset0:16 offset1:24
	ds_read2_b32 v[90:91], v15 offset0:49 offset1:57
	ds_read2_b32 v[92:93], v15 offset0:82 offset1:90
	ds_read2_b32 v[94:95], v15 offset0:115 offset1:123
	s_waitcnt lgkmcnt(4)
	v_cvt_pk_bf16_f32 v104, v72, v74
	v_cvt_pk_bf16_f32 v105, v76, v78
	v_cvt_pk_bf16_f32 v106, v80, v82
	v_cvt_pk_bf16_f32 v107, v84, v86
	v_cvt_pk_bf16_f32 v108, v73, v75
	v_cvt_pk_bf16_f32 v109, v77, v79
	v_cvt_pk_bf16_f32 v110, v81, v83
	v_cvt_pk_bf16_f32 v111, v85, v87
	ds_read2_b32 v[96:97], v15 offset0:148 offset1:156
	ds_read2_b32 v[98:99], v15 offset0:181 offset1:189
	ds_read2_b32 v[100:101], v15 offset0:214 offset1:222
	ds_read2_b32 v[102:103], v15 offset0:247 offset1:255
	global_store_dwordx4 v[126:127], v[104:107], off nt
	global_store_dwordx4 v[128:129], v[108:111], off nt
	s_waitcnt lgkmcnt(0)
	v_cvt_pk_bf16_f32 v112, v88, v90
	v_cvt_pk_bf16_f32 v113, v92, v94
	v_cvt_pk_bf16_f32 v114, v96, v98
	v_cvt_pk_bf16_f32 v115, v100, v102
	v_cvt_pk_bf16_f32 v116, v89, v91
	v_cvt_pk_bf16_f32 v117, v93, v95
	v_cvt_pk_bf16_f32 v118, v97, v99
	v_cvt_pk_bf16_f32 v119, v101, v103
	global_store_dwordx4 v[130:131], v[112:115], off nt
	global_store_dwordx4 v[132:133], v[116:119], off nt
	s_add_i32 s2, s2, 0x800
	s_cmp_lt_u32 s2, s101
	s_cbranch_scc1 .Ltk_gu_loop
	s_branch .LBB0_1705
.Ltk_busy:
	v_add_u32_e32 v2, 1, v0
	v_and_b32_e32 v3, 64, v200
	v_and_or_b32 v2, v2, 63, v3
	v_lshlrev_b32_e32 v20, 2, v2
	v_add_u32_e32 v2, 2, v0
	v_and_or_b32 v2, v2, 63, v3
	v_lshlrev_b32_e32 v21, 2, v2
	v_add_u32_e32 v2, 4, v0
	v_writelane_b32 v254, s71, 10
	v_writelane_b32 v253, s70, 53
	v_writelane_b32 v251, s64, 47
	v_and_or_b32 v2, v2, 63, v3
	v_lshlrev_b32_e32 v22, 2, v2
	v_writelane_b32 v251, s65, 48
	v_add_u32_e32 v2, 8, v0
	v_writelane_b32 v251, s66, 49
	v_and_or_b32 v2, v2, 63, v3
	v_writelane_b32 v251, s67, 50
	v_lshlrev_b32_e32 v23, 2, v2
	v_add_u32_e32 v2, 16, v0
	v_writelane_b32 v251, s68, 51
	v_and_or_b32 v2, v2, 63, v3
	v_writelane_b32 v251, s69, 52
	s_lshl_b32 s19, s18, 6
	v_lshlrev_b32_e32 v24, 2, v2
	v_and_or_b32 v2, v0, 63, v3
	v_writelane_b32 v251, s70, 53
	s_add_u32 s2, s4, 0x40aa8800
	v_lshlrev_b32_e32 v2, 2, v2
	v_writelane_b32 v251, s71, 54
	v_writelane_b32 v254, s2, 6
	s_addc_u32 s2, s5, 0
	v_xor_b32_e32 v25, 0x80, v2
	v_add_u32_e32 v2, -1, v0
	v_writelane_b32 v251, s72, 55
	v_writelane_b32 v254, s2, 13
	s_add_u32 s2, s4, 0x40bb8800
	v_and_or_b32 v2, v2, 63, v3
	v_writelane_b32 v251, s73, 56
	v_writelane_b32 v254, s2, 15
	s_addc_u32 s2, s5, 0
	v_lshlrev_b32_e32 v26, 2, v2
	v_add_u32_e32 v2, 62, v0
	v_writelane_b32 v251, s74, 57
	s_add_u32 s92, s4, 0x40cc8800
	v_and_or_b32 v2, v2, 63, v3
	v_writelane_b32 v251, s75, 58
	v_writelane_b32 v254, s2, 17
	s_addc_u32 s93, s5, 0
	v_cmp_eq_u32_e64 s[6:7], 63, v0
	v_lshlrev_b32_e32 v27, 2, v2
	v_add_u32_e32 v2, 60, v0
	v_writelane_b32 v251, s76, 59
	s_cmp_eq_u32 s18, 0
	v_writelane_b32 v254, s6, 19
	v_and_or_b32 v2, v2, 63, v3
	v_writelane_b32 v251, s77, 60
	s_cselect_b64 s[90:91], -1, 0
	v_writelane_b32 v254, s7, 20
	s_lshl_b32 s6, s18, 2
	v_lshlrev_b32_e32 v28, 2, v2
	v_add_u32_e32 v2, 56, v0
	v_writelane_b32 v251, s78, 61
	s_add_i32 s6, s6, 0
	v_and_or_b32 v2, v2, 63, v3
	v_writelane_b32 v251, s79, 62
	v_add_u32_e32 v6, s19, v0
	s_add_u32 s78, s4, 0x40d30c00
	v_lshlrev_b32_e32 v29, 2, v2
	v_add_u32_e32 v2, 48, v0
	s_addc_u32 s79, s5, 0
	v_add_u32_e32 v8, 0x880, v6
	v_and_or_b32 v2, v2, 63, v3
	s_movk_i32 s4, 0x7f
	v_lshlrev_b32_e32 v30, 2, v2
	s_cmp_gt_i32 s18, 0
	v_max_i32_e32 v2, 0x700, v8
	v_writelane_b32 v254, s6, 23
	v_cmp_lt_i32_e32 vcc, s4, v6
	v_cmp_lt_i32_e64 s[4:5], 0, v0
	s_cselect_b64 s[74:75], -1, 0
	s_cmp_gt_i32 s18, 1
	v_sub_u32_e32 v2, v2, v6
	v_writelane_b32 v254, s4, 21
	s_cselect_b64 s[96:97], -1, 0
	s_cmp_gt_i32 s18, 2
	v_add_u32_e32 v2, 0xfffff97f, v2
	v_writelane_b32 v254, s5, 22
	s_cselect_b64 s[88:89], -1, 0
	s_cmp_gt_i32 s18, 3
	v_lshrrev_b32_e32 v3, 9, v2
	s_movk_i32 s4, 0x1ff
	s_cselect_b64 s[70:71], -1, 0
	s_cmp_gt_i32 s18, 4
	v_add_u32_e32 v3, 1, v3
	v_cmp_lt_u32_e64 s[4:5], s4, v2
	s_cselect_b64 s[30:31], -1, 0
	s_cmp_gt_i32 s18, 5
	v_writelane_b32 v254, s4, 25
	v_and_b32_e32 v32, 0xfffffe, v3
	s_cselect_b64 s[80:81], -1, 0
	s_cmp_gt_i32 s18, 6
	v_writelane_b32 v254, s5, 26
	v_cmp_ne_u32_e64 s[4:5], v3, v32
	s_cselect_b64 s[72:73], -1, 0
	s_cmp_gt_i32 s18, 7
	v_writelane_b32 v254, s4, 11
	s_cselect_b64 s[76:77], -1, 0
	v_lshlrev_b32_e32 v15, 2, v0
	v_writelane_b32 v254, s5, 12
	s_lshl_b32 s4, s18, 8
	s_add_i32 s4, s4, 0
	v_lshl_add_u32 v16, v0, 4, 0
	v_cmp_gt_i32_e64 s[6:7], 63, v0
	v_cmp_gt_i32_e64 s[8:9], 62, v0
	v_cmp_gt_i32_e64 s[10:11], 60, v0
	v_cmp_gt_i32_e64 s[12:13], 56, v0
	v_cmp_gt_i32_e64 s[14:15], 48, v0
	v_cmp_gt_i32_e64 s[16:17], 32, v0
	v_cmp_gt_i32_e64 s[20:21], 2, v0
	v_cmp_gt_i32_e64 s[22:23], 4, v0
	v_cmp_gt_i32_e64 s[24:25], 8, v0
	v_cmp_gt_i32_e64 s[26:27], 16, v0
	v_not_b32_e32 v0, v0
	s_addk_i32 s4, 0x2000
	v_cmp_gt_i32_e64 s[2:3], s63, v6
	v_lshl_add_u32 v14, v6, 2, 0
	v_or_b32_e32 v17, 1, v15
	v_or_b32_e32 v18, 2, v15
	v_or_b32_e32 v19, 3, v15
	s_mov_b32 s33, s95
	v_subrev_u32_e32 v31, s19, v0
	v_add_u32_e32 v7, 0x200, v6
	v_lshl_add_u32 v33, v32, 9, v8
	v_add_u32_e32 v9, 0xa80, v6
	v_add_u32_e32 v34, s4, v15
	s_xor_b64 s[84:85], vcc, -1
	s_branch .LBB0_1534
